# A12 scan chunk summaries hand-written (batched loads, registers only, same op order) + RS_COMPUTE (R3,R8) 32 partial loads batched, same add order
# speedup vs baseline: 1.0364x; 1.0041x over previous
.LBB0_342:
	v_add_u32_e32 v0, s46, v0
	v_add_co_u32_e32 v4, vcc, 0xff500000, v2
	s_nop 1
	v_addc_co_u32_e32 v5, vcc, -1, v3, vcc
	global_load_dword v100, v[4:5], off
	v_add_co_u32_e32 v4, vcc, 0xff528000, v2
	s_nop 1
	v_addc_co_u32_e32 v5, vcc, -1, v3, vcc
	global_load_dword v101, v[4:5], off
	v_add_co_u32_e32 v4, vcc, 0xff550000, v2
	s_nop 1
	v_addc_co_u32_e32 v5, vcc, -1, v3, vcc
	global_load_dword v102, v[4:5], off
	v_add_co_u32_e32 v4, vcc, 0xff578000, v2
	s_nop 1
	v_addc_co_u32_e32 v5, vcc, -1, v3, vcc
	global_load_dword v103, v[4:5], off
	v_add_co_u32_e32 v4, vcc, 0xff5a0000, v2
	s_nop 1
	v_addc_co_u32_e32 v5, vcc, -1, v3, vcc
	global_load_dword v104, v[4:5], off
	v_add_co_u32_e32 v4, vcc, 0xff5c8000, v2
	s_nop 1
	v_addc_co_u32_e32 v5, vcc, -1, v3, vcc
	global_load_dword v105, v[4:5], off
	v_add_co_u32_e32 v4, vcc, 0xff5f0000, v2
	s_nop 1
	v_addc_co_u32_e32 v5, vcc, -1, v3, vcc
	global_load_dword v106, v[4:5], off
	v_add_co_u32_e32 v4, vcc, 0xff618000, v2
	s_nop 1
	v_addc_co_u32_e32 v5, vcc, -1, v3, vcc
	global_load_dword v107, v[4:5], off
	v_add_co_u32_e32 v4, vcc, 0xff640000, v2
	s_nop 1
	v_addc_co_u32_e32 v5, vcc, -1, v3, vcc
	global_load_dword v108, v[4:5], off
	v_add_co_u32_e32 v4, vcc, 0xff668000, v2
	s_nop 1
	v_addc_co_u32_e32 v5, vcc, -1, v3, vcc
	global_load_dword v109, v[4:5], off
	v_add_co_u32_e32 v4, vcc, 0xff690000, v2
	s_nop 1
	v_addc_co_u32_e32 v5, vcc, -1, v3, vcc
	global_load_dword v110, v[4:5], off
	v_add_co_u32_e32 v4, vcc, 0xff6b8000, v2
	s_nop 1
	v_addc_co_u32_e32 v5, vcc, -1, v3, vcc
	global_load_dword v111, v[4:5], off
	v_add_co_u32_e32 v4, vcc, 0xff6e0000, v2
	s_nop 1
	v_addc_co_u32_e32 v5, vcc, -1, v3, vcc
	global_load_dword v112, v[4:5], off
	v_add_co_u32_e32 v4, vcc, 0xff708000, v2
	s_nop 1
	v_addc_co_u32_e32 v5, vcc, -1, v3, vcc
	global_load_dword v113, v[4:5], off
	v_add_co_u32_e32 v4, vcc, 0xff730000, v2
	s_nop 1
	v_addc_co_u32_e32 v5, vcc, -1, v3, vcc
	global_load_dword v114, v[4:5], off
	v_add_co_u32_e32 v4, vcc, 0xff758000, v2
	s_nop 1
	v_addc_co_u32_e32 v5, vcc, -1, v3, vcc
	global_load_dword v115, v[4:5], off
	v_add_co_u32_e32 v4, vcc, 0xff780000, v2
	s_nop 1
	v_addc_co_u32_e32 v5, vcc, -1, v3, vcc
	global_load_dword v116, v[4:5], off
	v_add_co_u32_e32 v4, vcc, 0xff7a8000, v2
	s_nop 1
	v_addc_co_u32_e32 v5, vcc, -1, v3, vcc
	global_load_dword v117, v[4:5], off
	v_add_co_u32_e32 v4, vcc, 0xff7d0000, v2
	s_nop 1
	v_addc_co_u32_e32 v5, vcc, -1, v3, vcc
	global_load_dword v118, v[4:5], off
	v_add_co_u32_e32 v4, vcc, 0xff7f8000, v2
	s_nop 1
	v_addc_co_u32_e32 v5, vcc, -1, v3, vcc
	global_load_dword v119, v[4:5], off
	v_add_co_u32_e32 v4, vcc, 0xff820000, v2
	s_nop 1
	v_addc_co_u32_e32 v5, vcc, -1, v3, vcc
	global_load_dword v120, v[4:5], off
	v_add_co_u32_e32 v4, vcc, 0xff848000, v2
	s_nop 1
	v_addc_co_u32_e32 v5, vcc, -1, v3, vcc
	global_load_dword v121, v[4:5], off
	v_add_co_u32_e32 v4, vcc, 0xff870000, v2
	s_nop 1
	v_addc_co_u32_e32 v5, vcc, -1, v3, vcc
	global_load_dword v122, v[4:5], off
	v_add_co_u32_e32 v4, vcc, 0xff898000, v2
	s_nop 1
	v_addc_co_u32_e32 v5, vcc, -1, v3, vcc
	global_load_dword v123, v[4:5], off
	v_add_co_u32_e32 v4, vcc, 0xff8c0000, v2
	s_nop 1
	v_addc_co_u32_e32 v5, vcc, -1, v3, vcc
	global_load_dword v124, v[4:5], off
	v_add_co_u32_e32 v4, vcc, 0xff8e8000, v2
	s_nop 1
	v_addc_co_u32_e32 v5, vcc, -1, v3, vcc
	global_load_dword v125, v[4:5], off
	v_add_co_u32_e32 v4, vcc, 0xff910000, v2
	s_nop 1
	v_addc_co_u32_e32 v5, vcc, -1, v3, vcc
	global_load_dword v126, v[4:5], off
	v_add_co_u32_e32 v4, vcc, 0xff938000, v2
	s_nop 1
	v_addc_co_u32_e32 v5, vcc, -1, v3, vcc
	global_load_dword v127, v[4:5], off
	v_add_co_u32_e32 v4, vcc, 0xff960000, v2
	s_nop 1
	v_addc_co_u32_e32 v5, vcc, -1, v3, vcc
	global_load_dword v128, v[4:5], off
	v_add_co_u32_e32 v4, vcc, 0xff988000, v2
	s_nop 1
	v_addc_co_u32_e32 v5, vcc, -1, v3, vcc
	global_load_dword v129, v[4:5], off
	v_add_co_u32_e32 v4, vcc, 0xff9b0000, v2
	s_nop 1
	v_addc_co_u32_e32 v5, vcc, -1, v3, vcc
	global_load_dword v130, v[4:5], off
	v_add_co_u32_e32 v4, vcc, 0xff9d8000, v2
	s_nop 1
	v_addc_co_u32_e32 v5, vcc, -1, v3, vcc
	global_load_dword v131, v[4:5], off
	s_waitcnt vmcnt(31)
	v_add_f32_e32 v1, 0, v100
	s_waitcnt vmcnt(30)
	v_add_f32_e32 v1, v1, v101
	s_waitcnt vmcnt(29)
	v_add_f32_e32 v1, v1, v102
	s_waitcnt vmcnt(28)
	v_add_f32_e32 v1, v1, v103
	s_waitcnt vmcnt(27)
	v_add_f32_e32 v1, v1, v104
	s_waitcnt vmcnt(26)
	v_add_f32_e32 v1, v1, v105
	s_waitcnt vmcnt(25)
	v_add_f32_e32 v1, v1, v106
	s_waitcnt vmcnt(24)
	v_add_f32_e32 v1, v1, v107
	s_waitcnt vmcnt(23)
	v_add_f32_e32 v1, v1, v108
	s_waitcnt vmcnt(22)
	v_add_f32_e32 v1, v1, v109
	s_waitcnt vmcnt(21)
	v_add_f32_e32 v1, v1, v110
	s_waitcnt vmcnt(20)
	v_add_f32_e32 v1, v1, v111
	s_waitcnt vmcnt(19)
	v_add_f32_e32 v1, v1, v112
	s_waitcnt vmcnt(18)
	v_add_f32_e32 v1, v1, v113
	s_waitcnt vmcnt(17)
	v_add_f32_e32 v1, v1, v114
	s_waitcnt vmcnt(16)
	v_add_f32_e32 v1, v1, v115
	s_waitcnt vmcnt(15)
	v_add_f32_e32 v1, v1, v116
	s_waitcnt vmcnt(14)
	v_add_f32_e32 v1, v1, v117
	s_waitcnt vmcnt(13)
	v_add_f32_e32 v1, v1, v118
	s_waitcnt vmcnt(12)
	v_add_f32_e32 v1, v1, v119
	s_waitcnt vmcnt(11)
	v_add_f32_e32 v1, v1, v120
	s_waitcnt vmcnt(10)
	v_add_f32_e32 v1, v1, v121
	s_waitcnt vmcnt(9)
	v_add_f32_e32 v1, v1, v122
	s_waitcnt vmcnt(8)
	v_add_f32_e32 v1, v1, v123
	s_waitcnt vmcnt(7)
	v_add_f32_e32 v1, v1, v124
	s_waitcnt vmcnt(6)
	v_add_f32_e32 v1, v1, v125
	s_waitcnt vmcnt(5)
	v_add_f32_e32 v1, v1, v126
	s_waitcnt vmcnt(4)
	v_add_f32_e32 v1, v1, v127
	s_waitcnt vmcnt(3)
	v_add_f32_e32 v1, v1, v128
	s_waitcnt vmcnt(2)
	v_add_f32_e32 v1, v1, v129
	s_waitcnt vmcnt(1)
	v_add_f32_e32 v1, v1, v130
	s_waitcnt vmcnt(0)
	v_add_f32_e32 v1, v1, v131
	v_fmamk_f32 v1, v1, 0x3a000000, v196
	v_cmp_gt_f32_e32 vcc, s78, v1
	v_mul_f32_e32 v4, 0x4b800000, v1
	s_nop 0
	v_cndmask_b32_e32 v1, v1, v4, vcc
	v_rsq_f32_e32 v1, v1
	s_nop 0
	v_mul_f32_e32 v4, 0x45800000, v1
	v_cndmask_b32_e32 v1, v1, v4, vcc
	v_cmp_lt_i32_e32 vcc, s91, v0
	global_store_dword v[2:3], v1, off
	v_lshl_add_u64 v[2:3], v[2:3], 0, s[48:49]
	s_or_b64 s[50:51], vcc, s[50:51]
	s_andn2_b64 exec, exec, s[50:51]
	s_cbranch_execnz .LBB0_342

; __device__ __forceinline__ float fast_sigmoid(float x) { return __builtin_amdgcn_rcpf(1.f + __builtin_amdgcn_exp2f(-1.4426950408889634f * x)); }
; __device__ __forceinline__ float bf2f(unsigned short h) { return __uint_as_float(((unsigned)h) << 16); }
; __device__ __forceinline__ float bflo(unsigned w) { return __uint_as_float(w << 16); }
; __device__ __forceinline__ float bfhi(unsigned w) { return __uint_as_float(w & 0xffff0000u); }
; __device__ __forceinline__ void scan_coef(float r, float i, float u, float sp8, float& a, float& b) { const float la = -sp8 * r; a = __expf(la); b = __builtin_amdgcn_sqrtf(fmaxf((1.f - a) * (1.f + a), 0.f)) * (i * u); }
; __global__ void __launch_bounds__(512) mega_fwd(Params P) {
;     ...
;                     const int c = i - (N_MLA_L + N_MLA_S + N_A); const int ch = tid2; const int m0 = c * 32;
;                     const float spf = 8.f * log1pf(__expf(-lam[ch])), spb = 8.f * log1pf(__expf(-lam[512 + ch]));
;                     const float brf = b_rgr[ch], bif = b_rgi[ch], brb = b_rgr[512 + ch], bib = b_rgi[512 + ch];
;                     float pf = 1.f, ef = 0.f, pb = 1.f, eb = 0.f;
; #pragma unroll 4
;                     for (int t = 0; t < 32; ++t) { const bf16_t* gp = XN + (size_t)(m0 + t) * 2048; const float u = bf2f(UC[(size_t)(m0 + t) * 512 + ch]);
;                         const u32x2 g4 = *(const u32x2*)(gp + ch * 4);
;                         float a, b; scan_coef(pg8::fast_sigmoid(bflo(g4.x) + brf), pg8::fast_sigmoid(bfhi(g4.x) + bif), u, spf, a, b); ef = a * ef + b; pf *= a;
;                         scan_coef(pg8::fast_sigmoid(bflo(g4.y) + brb), pg8::fast_sigmoid(bfhi(g4.y) + bib), u, spb, a, b); eb += pb * b; pb *= a; }
.LBB0_999:
	global_load_dword v2, v[4:5], off
	s_ashr_i32 s45, s44, 31
	s_lshl_b64 s[38:39], s[44:45], 10
	v_lshl_add_u64 v[0:1], v[10:11], 0, s[38:39]
	s_lshl_b64 s[38:39], s[44:45], 12
	v_lshl_add_u64 v[16:17], v[12:13], 0, s[38:39]
	s_mov_b32 s39, 0x3f2aaaab
	s_mov_b32 s40, 0x3f317218
	v_mov_b32_e32 v30, 0x3ecc95a3
	s_mov_b32 s38, 0x7f800000
	v_mov_b32_e32 v32, 0x7f800000
	v_mov_b32_e32 v31, 0x7fc00000
	v_mov_b32_e32 v33, 0xff800000
	s_mov_b32 s41, 0x33800000
	v_mov_b32_e32 v18, 1.0
	s_mov_b32 s45, 0
	v_mov_b32_e32 v208, 0x7f800000
	v_mov_b32_e32 v197, 0x7fc00000
	v_mov_b32_e32 v252, 0xff800000
	s_waitcnt vmcnt(0)
	s_lshl_b32 s60, s44, 12
	s_mov_b32 s61, 0
	s_lshl_b32 s62, s44, 10
	s_mov_b32 s63, 0
	v_lshl_add_u64 v[34:35], v[12:13], 0, s[60:61]
	global_load_dwordx2 v[80:81], v[34:35], off
	v_lshl_add_u64 v[36:37], v[10:11], 0, s[62:63]
	global_load_ushort v144, v[36:37], off
	s_add_u32 s60, s60, 0x1000
	v_lshl_add_u64 v[34:35], v[12:13], 0, s[60:61]
	global_load_dwordx2 v[82:83], v[34:35], off
	global_load_ushort v145, v[36:37], off offset:1024
	s_add_u32 s60, s60, 0x1000
	v_lshl_add_u64 v[34:35], v[12:13], 0, s[60:61]
	global_load_dwordx2 v[84:85], v[34:35], off
	global_load_ushort v146, v[36:37], off offset:2048
	s_add_u32 s60, s60, 0x1000
	v_lshl_add_u64 v[34:35], v[12:13], 0, s[60:61]
	global_load_dwordx2 v[86:87], v[34:35], off
	global_load_ushort v147, v[36:37], off offset:3072
	s_add_u32 s60, s60, 0x1000
	s_add_u32 s62, s62, 0x1000
	v_lshl_add_u64 v[34:35], v[12:13], 0, s[60:61]
	global_load_dwordx2 v[88:89], v[34:35], off
	v_lshl_add_u64 v[36:37], v[10:11], 0, s[62:63]
	global_load_ushort v148, v[36:37], off
	s_add_u32 s60, s60, 0x1000
	v_lshl_add_u64 v[34:35], v[12:13], 0, s[60:61]
	global_load_dwordx2 v[90:91], v[34:35], off
	global_load_ushort v149, v[36:37], off offset:1024
	s_add_u32 s60, s60, 0x1000
	v_lshl_add_u64 v[34:35], v[12:13], 0, s[60:61]
	global_load_dwordx2 v[92:93], v[34:35], off
	global_load_ushort v150, v[36:37], off offset:2048
	s_add_u32 s60, s60, 0x1000
	v_lshl_add_u64 v[34:35], v[12:13], 0, s[60:61]
	global_load_dwordx2 v[94:95], v[34:35], off
	global_load_ushort v151, v[36:37], off offset:3072
	s_add_u32 s60, s60, 0x1000
	s_add_u32 s62, s62, 0x1000
	v_lshl_add_u64 v[34:35], v[12:13], 0, s[60:61]
	global_load_dwordx2 v[96:97], v[34:35], off
	v_lshl_add_u64 v[36:37], v[10:11], 0, s[62:63]
	global_load_ushort v152, v[36:37], off
	s_add_u32 s60, s60, 0x1000
	v_lshl_add_u64 v[34:35], v[12:13], 0, s[60:61]
	global_load_dwordx2 v[98:99], v[34:35], off
	global_load_ushort v153, v[36:37], off offset:1024
	s_add_u32 s60, s60, 0x1000
	v_lshl_add_u64 v[34:35], v[12:13], 0, s[60:61]
	global_load_dwordx2 v[100:101], v[34:35], off
	global_load_ushort v154, v[36:37], off offset:2048
	s_add_u32 s60, s60, 0x1000
	v_lshl_add_u64 v[34:35], v[12:13], 0, s[60:61]
	global_load_dwordx2 v[102:103], v[34:35], off
	global_load_ushort v155, v[36:37], off offset:3072
	s_add_u32 s60, s60, 0x1000
	s_add_u32 s62, s62, 0x1000
	v_lshl_add_u64 v[34:35], v[12:13], 0, s[60:61]
	global_load_dwordx2 v[104:105], v[34:35], off
	v_lshl_add_u64 v[36:37], v[10:11], 0, s[62:63]
	global_load_ushort v156, v[36:37], off
	s_add_u32 s60, s60, 0x1000
	v_lshl_add_u64 v[34:35], v[12:13], 0, s[60:61]
	global_load_dwordx2 v[106:107], v[34:35], off
	global_load_ushort v157, v[36:37], off offset:1024
	s_add_u32 s60, s60, 0x1000
	v_lshl_add_u64 v[34:35], v[12:13], 0, s[60:61]
	global_load_dwordx2 v[108:109], v[34:35], off
	global_load_ushort v158, v[36:37], off offset:2048
	s_add_u32 s60, s60, 0x1000
	v_lshl_add_u64 v[34:35], v[12:13], 0, s[60:61]
	global_load_dwordx2 v[110:111], v[34:35], off
	global_load_ushort v159, v[36:37], off offset:3072
	s_add_u32 s60, s60, 0x1000
	s_add_u32 s62, s62, 0x1000
	v_mul_f32_e32 v2, 0xbfb8aa3b, v2
	v_exp_f32_e32 v19, v2
	s_nop 0
	v_add_f32_e32 v20, 1.0, v19
	v_add_f32_e32 v2, -1.0, v20
	v_sub_f32_e32 v3, v2, v20
	v_add_f32_e32 v3, 1.0, v3
	v_sub_f32_e32 v2, v19, v2
	v_add_f32_e32 v21, v2, v3
	v_frexp_mant_f32_e32 v2, v20
	v_cmp_gt_f32_e32 vcc, s39, v2
	v_cvt_f64_f32_e32 v[2:3], v20
	v_frexp_exp_i32_f64_e32 v2, v[2:3]
	v_subbrev_co_u32_e32 v2, vcc, 0, v2, vcc
	v_sub_u32_e32 v3, 0, v2
	v_ldexp_f32 v20, v20, v3
	v_ldexp_f32 v3, v21, v3
	v_add_f32_e32 v21, -1.0, v20
	v_add_f32_e32 v22, 1.0, v21
	v_sub_f32_e32 v22, v20, v22
	v_add_f32_e32 v22, v3, v22
	v_add_f32_e32 v23, v21, v22
	v_sub_f32_e32 v21, v23, v21
	v_sub_f32_e32 v21, v22, v21
	v_add_f32_e32 v22, 1.0, v20
	v_add_f32_e32 v24, -1.0, v22
	v_sub_f32_e32 v20, v20, v24
	v_add_f32_e32 v3, v3, v20
	v_add_f32_e32 v20, v22, v3
	v_sub_f32_e32 v22, v20, v22
	v_sub_f32_e32 v3, v3, v22
	v_rcp_f32_e32 v22, v20
	v_cvt_f32_i32_e32 v2, v2
	v_cmp_neq_f32_e32 vcc, s38, v19
	v_mul_f32_e32 v24, v23, v22
	v_mul_f32_e32 v25, v20, v24
	v_fma_f32 v26, v24, v20, -v25
	v_fmac_f32_e32 v26, v24, v3
	v_add_f32_e32 v27, v25, v26
	v_sub_f32_e32 v28, v23, v27
	v_sub_f32_e32 v23, v23, v28
	v_sub_f32_e32 v25, v27, v25
	v_sub_f32_e32 v23, v23, v27
	v_add_f32_e32 v21, v21, v23
	v_sub_f32_e32 v23, v25, v26
	v_add_f32_e32 v21, v23, v21
	v_add_f32_e32 v23, v28, v21
	v_mul_f32_e32 v25, v22, v23
	v_mul_f32_e32 v26, v20, v25
	v_fma_f32 v20, v25, v20, -v26
	v_fmac_f32_e32 v20, v25, v3
	v_sub_f32_e32 v3, v28, v23
	v_add_f32_e32 v3, v21, v3
	v_add_f32_e32 v21, v26, v20
	v_sub_f32_e32 v27, v23, v21
	v_sub_f32_e32 v23, v23, v27
	v_sub_f32_e32 v26, v21, v26
	v_sub_f32_e32 v21, v23, v21
	v_add_f32_e32 v3, v3, v21
	v_sub_f32_e32 v20, v26, v20
	v_add_f32_e32 v3, v20, v3
	v_add_f32_e32 v20, v24, v25
	v_add_f32_e32 v3, v27, v3
	v_sub_f32_e32 v21, v20, v24
	v_mul_f32_e32 v3, v22, v3
	v_sub_f32_e32 v21, v25, v21
	v_add_f32_e32 v3, v21, v3
	v_mul_f32_e32 v24, 0x3f317218, v2
	v_add_f32_e32 v21, v20, v3
	v_fma_f32 v25, v2, s40, -v24
	v_mul_f32_e32 v22, v21, v21
	v_fmac_f32_e32 v25, 0xb102e308, v2
	v_sub_f32_e32 v2, v21, v20
	v_fmamk_f32 v23, v22, 0x3e9b6dac, v30
	v_sub_f32_e32 v2, v3, v2
	v_add_f32_e32 v3, v24, v25
	v_fmaak_f32 v23, v22, v23, 0x3f2aaada
	v_sub_f32_e32 v20, v3, v24
	v_ldexp_f32 v24, v21, 1
	v_mul_f32_e32 v21, v21, v22
	v_mul_f32_e32 v21, v21, v23
	v_add_f32_e32 v22, v24, v21
	v_sub_f32_e32 v23, v22, v24
	v_ldexp_f32 v2, v2, 1
	v_sub_f32_e32 v21, v21, v23
	v_add_f32_e32 v2, v2, v21
	v_add_f32_e32 v21, v22, v2
	v_sub_f32_e32 v22, v21, v22
	v_sub_f32_e32 v2, v2, v22
	v_add_f32_e32 v22, v3, v21
	v_sub_f32_e32 v23, v22, v3
	v_sub_f32_e32 v24, v22, v23
	v_sub_f32_e32 v20, v25, v20
	v_sub_f32_e32 v3, v3, v24
	v_sub_f32_e32 v21, v21, v23
	v_add_f32_e32 v3, v21, v3
	v_add_f32_e32 v21, v20, v2
	v_sub_f32_e32 v23, v21, v20
	v_sub_f32_e32 v24, v21, v23
	v_sub_f32_e32 v20, v20, v24
	v_sub_f32_e32 v2, v2, v23
	v_add_f32_e32 v3, v21, v3
	v_add_f32_e32 v2, v2, v20
	v_add_f32_e32 v20, v22, v3
	v_sub_f32_e32 v21, v20, v22
	v_sub_f32_e32 v3, v3, v21
	v_add_f32_e32 v2, v2, v3
	global_load_dword v3, v[4:5], off offset:2048
	v_add_f32_e32 v2, v20, v2
	v_cndmask_b32_e32 v2, v32, v2, vcc
	v_cmp_ngt_f32_e32 vcc, -1.0, v19
	s_waitcnt vmcnt(0)
; __global__ void __launch_bounds__(512) mega_fwd(Params P) {
;     ...
;                     const float spf = 8.f * log1pf(__expf(-lam[ch])), spb = 8.f * log1pf(__expf(-lam[512 + ch]));
;                     const float brf = b_rgr[ch], bif = b_rgi[ch], brb = b_rgr[512 + ch], bib = b_rgi[512 + ch];
;                     float pf = 1.f, ef = 0.f, pb = 1.f, eb = 0.f;
	v_mul_f32_e32 v3, 0xbfb8aa3b, v3
	v_exp_f32_e32 v3, v3
	v_cndmask_b32_e32 v2, v31, v2, vcc
	v_cmp_neq_f32_e32 vcc, -1.0, v19
	v_add_f32_e32 v22, 1.0, v3
	s_nop 0
	v_cndmask_b32_e32 v2, v33, v2, vcc
	v_cmp_lt_f32_e64 vcc, |v19|, s41
	s_nop 1
	v_cndmask_b32_e32 v2, v2, v19, vcc
	v_add_f32_e32 v19, -1.0, v22
	v_sub_f32_e32 v20, v19, v22
	v_add_f32_e32 v20, 1.0, v20
	v_sub_f32_e32 v19, v3, v19
	v_add_f32_e32 v23, v19, v20
	v_frexp_mant_f32_e32 v19, v22
	v_cvt_f64_f32_e32 v[20:21], v22
	v_cmp_gt_f32_e32 vcc, s39, v19
	v_frexp_exp_i32_f64_e32 v19, v[20:21]
	s_nop 0
	v_subbrev_co_u32_e32 v19, vcc, 0, v19, vcc
	v_sub_u32_e32 v20, 0, v19
	v_ldexp_f32 v21, v22, v20
	v_add_f32_e32 v22, -1.0, v21
	v_ldexp_f32 v20, v23, v20
	v_add_f32_e32 v23, 1.0, v22
	v_sub_f32_e32 v23, v21, v23
	v_add_f32_e32 v23, v20, v23
	v_add_f32_e32 v24, v22, v23
	v_sub_f32_e32 v22, v24, v22
	v_sub_f32_e32 v22, v23, v22
	v_add_f32_e32 v23, 1.0, v21
	v_add_f32_e32 v25, -1.0, v23
	v_sub_f32_e32 v21, v21, v25
	v_add_f32_e32 v20, v20, v21
	v_add_f32_e32 v21, v23, v20
	v_sub_f32_e32 v23, v21, v23
	v_sub_f32_e32 v20, v20, v23
	v_rcp_f32_e32 v23, v21
	v_cvt_f32_i32_e32 v19, v19
	v_cmp_neq_f32_e32 vcc, s38, v3
	v_mul_f32_e32 v25, v24, v23
	v_mul_f32_e32 v26, v21, v25
	v_fma_f32 v27, v25, v21, -v26
	v_fmac_f32_e32 v27, v25, v20
	v_add_f32_e32 v28, v26, v27
	v_sub_f32_e32 v29, v24, v28
	v_sub_f32_e32 v24, v24, v29
	v_sub_f32_e32 v26, v28, v26
	v_sub_f32_e32 v24, v24, v28
	v_add_f32_e32 v22, v22, v24
	v_sub_f32_e32 v24, v26, v27
	v_add_f32_e32 v22, v24, v22
	v_add_f32_e32 v24, v29, v22
	v_mul_f32_e32 v26, v23, v24
	v_mul_f32_e32 v27, v21, v26
	v_fma_f32 v21, v26, v21, -v27
	v_fmac_f32_e32 v21, v26, v20
	v_sub_f32_e32 v20, v29, v24
	v_add_f32_e32 v20, v22, v20
	v_add_f32_e32 v22, v27, v21
	v_sub_f32_e32 v28, v24, v22
	v_sub_f32_e32 v24, v24, v28
	v_sub_f32_e32 v27, v22, v27
	v_sub_f32_e32 v22, v24, v22
	v_add_f32_e32 v20, v20, v22
	v_sub_f32_e32 v21, v27, v21
	v_add_f32_e32 v20, v21, v20
	v_add_f32_e32 v21, v25, v26
	v_add_f32_e32 v20, v28, v20
	v_sub_f32_e32 v22, v21, v25
	v_mul_f32_e32 v20, v23, v20
	v_sub_f32_e32 v22, v26, v22
	v_add_f32_e32 v20, v22, v20
	v_mul_f32_e32 v25, 0x3f317218, v19
	v_add_f32_e32 v22, v21, v20
	v_fma_f32 v26, v19, s40, -v25
	v_mul_f32_e32 v23, v22, v22
	v_fmac_f32_e32 v26, 0xb102e308, v19
	v_sub_f32_e32 v19, v22, v21
	v_fmamk_f32 v24, v23, 0x3e9b6dac, v30
	v_sub_f32_e32 v19, v20, v19
	v_add_f32_e32 v20, v25, v26
	v_fmaak_f32 v24, v23, v24, 0x3f2aaada
	v_sub_f32_e32 v21, v20, v25
	v_ldexp_f32 v25, v22, 1
	v_mul_f32_e32 v22, v22, v23
	v_mul_f32_e32 v22, v22, v24
	v_add_f32_e32 v23, v25, v22
	v_sub_f32_e32 v24, v23, v25
	v_ldexp_f32 v19, v19, 1
	v_sub_f32_e32 v22, v22, v24
	v_add_f32_e32 v19, v19, v22
	v_add_f32_e32 v22, v23, v19
	v_sub_f32_e32 v23, v22, v23
	v_sub_f32_e32 v19, v19, v23
	v_add_f32_e32 v23, v20, v22
	v_sub_f32_e32 v24, v23, v20
	v_sub_f32_e32 v25, v23, v24
	v_sub_f32_e32 v21, v26, v21
	v_sub_f32_e32 v20, v20, v25
	v_sub_f32_e32 v22, v22, v24
	v_add_f32_e32 v20, v22, v20
	v_add_f32_e32 v22, v21, v19
	v_sub_f32_e32 v24, v22, v21
	v_sub_f32_e32 v25, v22, v24
	v_sub_f32_e32 v21, v21, v25
	v_sub_f32_e32 v19, v19, v24
	v_add_f32_e32 v20, v22, v20
	v_add_f32_e32 v19, v19, v21
	v_add_f32_e32 v21, v23, v20
	v_sub_f32_e32 v22, v21, v23
	v_sub_f32_e32 v20, v20, v22
	v_add_f32_e32 v19, v19, v20
	v_add_f32_e32 v19, v21, v19
	global_load_dword v20, v[6:7], off
	global_load_dword v21, v[8:9], off
	global_load_dword v22, v[6:7], off offset:2048
	global_load_dword v23, v[8:9], off offset:2048
	v_cndmask_b32_e32 v19, v32, v19, vcc
	v_cmp_ngt_f32_e32 vcc, -1.0, v3
	v_mul_f32_e32 v24, 0xc1000000, v2
	v_mov_b32_e32 v2, 0
	v_cndmask_b32_e32 v19, v31, v19, vcc
	v_cmp_neq_f32_e32 vcc, -1.0, v3
	s_nop 1
	v_cndmask_b32_e32 v19, v33, v19, vcc
	v_cmp_lt_f32_e64 vcc, |v3|, s41
	s_nop 1
	v_cndmask_b32_e32 v3, v19, v3, vcc
	v_mul_f32_e32 v25, 0xc1000000, v3
	v_mov_b32_e32 v3, v2
	v_mov_b32_e32 v19, v18
	v_lshl_add_u64 v[34:35], v[12:13], 0, s[60:61]
	global_load_dwordx2 v[112:113], v[34:35], off
	v_lshl_add_u64 v[36:37], v[10:11], 0, s[62:63]
	global_load_ushort v160, v[36:37], off
	s_add_u32 s60, s60, 0x1000
	v_lshl_add_u64 v[34:35], v[12:13], 0, s[60:61]
	global_load_dwordx2 v[114:115], v[34:35], off
	global_load_ushort v161, v[36:37], off offset:1024
	s_add_u32 s60, s60, 0x1000
	v_lshl_add_u64 v[34:35], v[12:13], 0, s[60:61]
	global_load_dwordx2 v[116:117], v[34:35], off
	global_load_ushort v162, v[36:37], off offset:2048
	s_add_u32 s60, s60, 0x1000
	v_lshl_add_u64 v[34:35], v[12:13], 0, s[60:61]
	global_load_dwordx2 v[118:119], v[34:35], off
	global_load_ushort v163, v[36:37], off offset:3072
	s_add_u32 s60, s60, 0x1000
	s_add_u32 s62, s62, 0x1000
	v_lshl_add_u64 v[34:35], v[12:13], 0, s[60:61]
	global_load_dwordx2 v[120:121], v[34:35], off
	v_lshl_add_u64 v[36:37], v[10:11], 0, s[62:63]
	global_load_ushort v164, v[36:37], off
	s_add_u32 s60, s60, 0x1000
	v_lshl_add_u64 v[34:35], v[12:13], 0, s[60:61]
	global_load_dwordx2 v[122:123], v[34:35], off
	global_load_ushort v165, v[36:37], off offset:1024
	s_add_u32 s60, s60, 0x1000
	v_lshl_add_u64 v[34:35], v[12:13], 0, s[60:61]
	global_load_dwordx2 v[124:125], v[34:35], off
	global_load_ushort v166, v[36:37], off offset:2048
	s_add_u32 s60, s60, 0x1000
	v_lshl_add_u64 v[34:35], v[12:13], 0, s[60:61]
	global_load_dwordx2 v[126:127], v[34:35], off
	global_load_ushort v167, v[36:37], off offset:3072
	s_add_u32 s60, s60, 0x1000
	s_add_u32 s62, s62, 0x1000
	v_lshl_add_u64 v[34:35], v[12:13], 0, s[60:61]
	global_load_dwordx2 v[128:129], v[34:35], off
	v_lshl_add_u64 v[36:37], v[10:11], 0, s[62:63]
	global_load_ushort v168, v[36:37], off
	s_add_u32 s60, s60, 0x1000
	v_lshl_add_u64 v[34:35], v[12:13], 0, s[60:61]
	global_load_dwordx2 v[130:131], v[34:35], off
	global_load_ushort v169, v[36:37], off offset:1024
	s_add_u32 s60, s60, 0x1000
	v_lshl_add_u64 v[34:35], v[12:13], 0, s[60:61]
	global_load_dwordx2 v[132:133], v[34:35], off
	global_load_ushort v170, v[36:37], off offset:2048
	s_add_u32 s60, s60, 0x1000
	v_lshl_add_u64 v[34:35], v[12:13], 0, s[60:61]
	global_load_dwordx2 v[134:135], v[34:35], off
	global_load_ushort v171, v[36:37], off offset:3072
	s_add_u32 s60, s60, 0x1000
	s_add_u32 s62, s62, 0x1000
	v_lshl_add_u64 v[34:35], v[12:13], 0, s[60:61]
	global_load_dwordx2 v[136:137], v[34:35], off
	v_lshl_add_u64 v[36:37], v[10:11], 0, s[62:63]
	global_load_ushort v172, v[36:37], off
	s_add_u32 s60, s60, 0x1000
	v_lshl_add_u64 v[34:35], v[12:13], 0, s[60:61]
	global_load_dwordx2 v[138:139], v[34:35], off
	global_load_ushort v173, v[36:37], off offset:1024
	s_add_u32 s60, s60, 0x1000
	v_lshl_add_u64 v[34:35], v[12:13], 0, s[60:61]
	global_load_dwordx2 v[140:141], v[34:35], off
	global_load_ushort v174, v[36:37], off offset:2048
	s_add_u32 s60, s60, 0x1000
	v_lshl_add_u64 v[34:35], v[12:13], 0, s[60:61]
	global_load_dwordx2 v[142:143], v[34:35], off
	global_load_ushort v175, v[36:37], off offset:3072
	s_add_u32 s60, s60, 0x1000
	s_add_u32 s62, s62, 0x1000
	s_waitcnt vmcnt(32)
; __device__ __forceinline__ float fast_sigmoid(float x) { return __builtin_amdgcn_rcpf(1.f + __builtin_amdgcn_exp2f(-1.4426950408889634f * x)); }
; __device__ __forceinline__ float bf2f(unsigned short h) { return __uint_as_float(((unsigned)h) << 16); }
; __device__ __forceinline__ float bflo(unsigned w) { return __uint_as_float(w << 16); }
; __device__ __forceinline__ float bfhi(unsigned w) { return __uint_as_float(w & 0xffff0000u); }
; __device__ __forceinline__ void scan_coef(float r, float i, float u, float sp8, float& a, float& b) { const float la = -sp8 * r; a = __expf(la); b = __builtin_amdgcn_sqrtf(fmaxf((1.f - a) * (1.f + a), 0.f)) * (i * u); }
; __global__ void __launch_bounds__(512) mega_fwd(Params P) {
;     ...
;                     for (int t = 0; t < 32; ++t) { const bf16_t* gp = XN + (size_t)(m0 + t) * 2048; const float u = bf2f(UC[(size_t)(m0 + t) * 512 + ch]);
;                         const u32x2 g4 = *(const u32x2*)(gp + ch * 4);
;                         float a, b; scan_coef(pg8::fast_sigmoid(bflo(g4.x) + brf), pg8::fast_sigmoid(bfhi(g4.x) + bif), u, spf, a, b); ef = a * ef + b; pf *= a;
;                         scan_coef(pg8::fast_sigmoid(bflo(g4.y) + brb), pg8::fast_sigmoid(bfhi(g4.y) + bib), u, spb, a, b); eb += pb * b; pb *= a; }
	v_lshlrev_b32_e32 v48, 16, v80
	v_lshlrev_b32_e32 v51, 16, v82
	v_lshlrev_b32_e32 v54, 16, v84
	v_lshlrev_b32_e32 v57, 16, v86
	v_and_b32_e32 v49, 0xffff0000, v80
	v_and_b32_e32 v52, 0xffff0000, v82
	v_and_b32_e32 v55, 0xffff0000, v84
	v_and_b32_e32 v58, 0xffff0000, v86
	v_add_f32_e32 v48, v20, v48
	v_add_f32_e32 v51, v20, v51
	v_add_f32_e32 v54, v20, v54
	v_add_f32_e32 v57, v20, v57
	v_add_f32_e32 v49, v21, v49
	v_add_f32_e32 v52, v21, v52
	v_add_f32_e32 v55, v21, v55
	v_add_f32_e32 v58, v21, v58
	v_mul_f32_e32 v48, 0xbfb8aa3b, v48
	v_mul_f32_e32 v51, 0xbfb8aa3b, v51
	v_mul_f32_e32 v54, 0xbfb8aa3b, v54
	v_mul_f32_e32 v57, 0xbfb8aa3b, v57
	v_mul_f32_e32 v49, 0xbfb8aa3b, v49
	v_mul_f32_e32 v52, 0xbfb8aa3b, v52
	v_mul_f32_e32 v55, 0xbfb8aa3b, v55
	v_mul_f32_e32 v58, 0xbfb8aa3b, v58
	v_exp_f32_e32 v48, v48
	v_exp_f32_e32 v51, v51
	v_exp_f32_e32 v54, v54
	v_exp_f32_e32 v57, v57
	v_exp_f32_e32 v49, v49
	v_exp_f32_e32 v52, v52
	v_exp_f32_e32 v55, v55
	v_exp_f32_e32 v58, v58
	v_lshlrev_b32_e32 v50, 16, v144
	v_lshlrev_b32_e32 v53, 16, v145
	v_lshlrev_b32_e32 v56, 16, v146
	v_lshlrev_b32_e32 v59, 16, v147
	v_add_f32_e32 v48, 1.0, v48
	v_add_f32_e32 v51, 1.0, v51
	v_add_f32_e32 v54, 1.0, v54
	v_add_f32_e32 v57, 1.0, v57
	v_add_f32_e32 v49, 1.0, v49
	v_add_f32_e32 v52, 1.0, v52
	v_add_f32_e32 v55, 1.0, v55
	v_add_f32_e32 v58, 1.0, v58
	v_rcp_f32_e32 v48, v48
	v_rcp_f32_e32 v51, v51
	v_rcp_f32_e32 v54, v54
	v_rcp_f32_e32 v57, v57
	v_rcp_f32_e32 v49, v49
	v_rcp_f32_e32 v52, v52
	v_rcp_f32_e32 v55, v55
	v_rcp_f32_e32 v58, v58
	v_mul_f32_e32 v48, v24, v48
	v_mul_f32_e32 v51, v24, v51
	v_mul_f32_e32 v54, v24, v54
	v_mul_f32_e32 v57, v24, v57
	v_mul_f32_e32 v49, v49, v50
	v_mul_f32_e32 v52, v52, v53
	v_mul_f32_e32 v55, v55, v56
	v_mul_f32_e32 v58, v58, v59
	v_mul_f32_e32 v48, 0x3fb8aa3b, v48
	v_mul_f32_e32 v51, 0x3fb8aa3b, v51
	v_mul_f32_e32 v54, 0x3fb8aa3b, v54
	v_mul_f32_e32 v57, 0x3fb8aa3b, v57
	v_exp_f32_e32 v48, v48
	v_exp_f32_e32 v51, v51
	v_exp_f32_e32 v54, v54
	v_exp_f32_e32 v57, v57
	v_sub_f32_e32 v50, 1.0, v48
	v_sub_f32_e32 v53, 1.0, v51
	v_sub_f32_e32 v56, 1.0, v54
	v_sub_f32_e32 v59, 1.0, v57
	v_add_f32_e32 v80, 1.0, v48
	v_add_f32_e32 v82, 1.0, v51
	v_add_f32_e32 v84, 1.0, v54
	v_add_f32_e32 v86, 1.0, v57
	v_mul_f32_e32 v50, v50, v80
	v_mul_f32_e32 v53, v53, v82
	v_mul_f32_e32 v56, v56, v84
	v_mul_f32_e32 v59, v59, v86
	v_max_f32_e32 v50, 0, v50
	v_max_f32_e32 v53, 0, v53
	v_max_f32_e32 v56, 0, v56
	v_max_f32_e32 v59, 0, v59
	v_sqrt_f32_e32 v50, v50
	v_sqrt_f32_e32 v53, v53
	v_sqrt_f32_e32 v56, v56
	v_sqrt_f32_e32 v59, v59
	v_lshlrev_b32_e32 v60, 16, v81
	v_lshlrev_b32_e32 v63, 16, v83
	v_lshlrev_b32_e32 v66, 16, v85
	v_lshlrev_b32_e32 v69, 16, v87
	v_and_b32_e32 v61, 0xffff0000, v81
	v_and_b32_e32 v64, 0xffff0000, v83
	v_and_b32_e32 v67, 0xffff0000, v85
	v_and_b32_e32 v70, 0xffff0000, v87
	v_add_f32_e32 v60, v22, v60
	v_add_f32_e32 v63, v22, v63
	v_add_f32_e32 v66, v22, v66
	v_add_f32_e32 v69, v22, v69
	v_add_f32_e32 v61, v23, v61
	v_add_f32_e32 v64, v23, v64
	v_add_f32_e32 v67, v23, v67
	v_add_f32_e32 v70, v23, v70
	v_mul_f32_e32 v60, 0xbfb8aa3b, v60
	v_mul_f32_e32 v63, 0xbfb8aa3b, v63
	v_mul_f32_e32 v66, 0xbfb8aa3b, v66
	v_mul_f32_e32 v69, 0xbfb8aa3b, v69
	v_mul_f32_e32 v61, 0xbfb8aa3b, v61
	v_mul_f32_e32 v64, 0xbfb8aa3b, v64
	v_mul_f32_e32 v67, 0xbfb8aa3b, v67
	v_mul_f32_e32 v70, 0xbfb8aa3b, v70
	v_exp_f32_e32 v60, v60
	v_exp_f32_e32 v63, v63
	v_exp_f32_e32 v66, v66
	v_exp_f32_e32 v69, v69
	v_exp_f32_e32 v61, v61
	v_exp_f32_e32 v64, v64
	v_exp_f32_e32 v67, v67
	v_exp_f32_e32 v70, v70
	v_lshlrev_b32_e32 v62, 16, v144
	v_lshlrev_b32_e32 v65, 16, v145
	v_lshlrev_b32_e32 v68, 16, v146
	v_lshlrev_b32_e32 v71, 16, v147
	v_add_f32_e32 v60, 1.0, v60
	v_add_f32_e32 v63, 1.0, v63
	v_add_f32_e32 v66, 1.0, v66
	v_add_f32_e32 v69, 1.0, v69
	v_add_f32_e32 v61, 1.0, v61
	v_add_f32_e32 v64, 1.0, v64
	v_add_f32_e32 v67, 1.0, v67
	v_add_f32_e32 v70, 1.0, v70
	v_rcp_f32_e32 v60, v60
	v_rcp_f32_e32 v63, v63
	v_rcp_f32_e32 v66, v66
	v_rcp_f32_e32 v69, v69
	v_rcp_f32_e32 v61, v61
	v_rcp_f32_e32 v64, v64
	v_rcp_f32_e32 v67, v67
	v_rcp_f32_e32 v70, v70
	v_mul_f32_e32 v60, v25, v60
	v_mul_f32_e32 v63, v25, v63
	v_mul_f32_e32 v66, v25, v66
	v_mul_f32_e32 v69, v25, v69
	v_mul_f32_e32 v61, v61, v62
	v_mul_f32_e32 v64, v64, v65
	v_mul_f32_e32 v67, v67, v68
	v_mul_f32_e32 v70, v70, v71
	v_mul_f32_e32 v60, 0x3fb8aa3b, v60
	v_mul_f32_e32 v63, 0x3fb8aa3b, v63
	v_mul_f32_e32 v66, 0x3fb8aa3b, v66
	v_mul_f32_e32 v69, 0x3fb8aa3b, v69
	v_exp_f32_e32 v60, v60
	v_exp_f32_e32 v63, v63
	v_exp_f32_e32 v66, v66
	v_exp_f32_e32 v69, v69
	v_sub_f32_e32 v62, 1.0, v60
	v_sub_f32_e32 v65, 1.0, v63
	v_sub_f32_e32 v68, 1.0, v66
	v_sub_f32_e32 v71, 1.0, v69
	v_add_f32_e32 v81, 1.0, v60
	v_add_f32_e32 v83, 1.0, v63
	v_add_f32_e32 v85, 1.0, v66
	v_add_f32_e32 v87, 1.0, v69
	v_mul_f32_e32 v62, v62, v81
	v_mul_f32_e32 v65, v65, v83
	v_mul_f32_e32 v68, v68, v85
	v_mul_f32_e32 v71, v71, v87
	v_max_f32_e32 v62, 0, v62
	v_max_f32_e32 v65, 0, v65
	v_max_f32_e32 v68, 0, v68
	v_max_f32_e32 v71, 0, v71
	v_sqrt_f32_e32 v62, v62
	v_sqrt_f32_e32 v65, v65
	v_sqrt_f32_e32 v68, v68
	v_sqrt_f32_e32 v71, v71
	v_nop
	v_nop
	v_nop
	v_nop
	v_mul_f32_e32 v61, v61, v62
	v_mul_f32_e32 v64, v64, v65
	v_mul_f32_e32 v67, v67, v68
	v_mul_f32_e32 v70, v70, v71
	v_mul_f32_e32 v2, v2, v48
	v_fma_f32 v2, v49, v50, v2
	v_fma_f32 v3, v61, v19, v3
	v_mul_f32_e32 v18, v18, v48
	v_mul_f32_e32 v19, v19, v60
	v_mul_f32_e32 v2, v2, v51
	v_fma_f32 v2, v52, v53, v2
	v_fma_f32 v3, v64, v19, v3
	v_mul_f32_e32 v18, v18, v51
	v_mul_f32_e32 v19, v19, v63
	v_mul_f32_e32 v2, v2, v54
	v_fma_f32 v2, v55, v56, v2
	v_fma_f32 v3, v67, v19, v3
; __device__ __forceinline__ float fast_sigmoid(float x) { return __builtin_amdgcn_rcpf(1.f + __builtin_amdgcn_exp2f(-1.4426950408889634f * x)); }
; __device__ __forceinline__ float bf2f(unsigned short h) { return __uint_as_float(((unsigned)h) << 16); }
; __device__ __forceinline__ float bflo(unsigned w) { return __uint_as_float(w << 16); }
; __device__ __forceinline__ float bfhi(unsigned w) { return __uint_as_float(w & 0xffff0000u); }
; __device__ __forceinline__ void scan_coef(float r, float i, float u, float sp8, float& a, float& b) { const float la = -sp8 * r; a = __expf(la); b = __builtin_amdgcn_sqrtf(fmaxf((1.f - a) * (1.f + a), 0.f)) * (i * u); }
; __global__ void __launch_bounds__(512) mega_fwd(Params P) {
;     ...
;                     for (int t = 0; t < 32; ++t) { const bf16_t* gp = XN + (size_t)(m0 + t) * 2048; const float u = bf2f(UC[(size_t)(m0 + t) * 512 + ch]);
;                         const u32x2 g4 = *(const u32x2*)(gp + ch * 4);
;                         float a, b; scan_coef(pg8::fast_sigmoid(bflo(g4.x) + brf), pg8::fast_sigmoid(bfhi(g4.x) + bif), u, spf, a, b); ef = a * ef + b; pf *= a;
;                         scan_coef(pg8::fast_sigmoid(bflo(g4.y) + brb), pg8::fast_sigmoid(bfhi(g4.y) + bib), u, spb, a, b); eb += pb * b; pb *= a; }
	v_mul_f32_e32 v18, v18, v54
	v_mul_f32_e32 v19, v19, v66
	v_mul_f32_e32 v2, v2, v57
	v_fma_f32 v2, v58, v59, v2
	v_fma_f32 v3, v70, v19, v3
	v_mul_f32_e32 v18, v18, v57
	v_mul_f32_e32 v19, v19, v69
	v_lshlrev_b32_e32 v48, 16, v88
	v_lshlrev_b32_e32 v51, 16, v90
	v_lshlrev_b32_e32 v54, 16, v92
	v_lshlrev_b32_e32 v57, 16, v94
	v_and_b32_e32 v49, 0xffff0000, v88
	v_and_b32_e32 v52, 0xffff0000, v90
	v_and_b32_e32 v55, 0xffff0000, v92
	v_and_b32_e32 v58, 0xffff0000, v94
	v_add_f32_e32 v48, v20, v48
	v_add_f32_e32 v51, v20, v51
	v_add_f32_e32 v54, v20, v54
	v_add_f32_e32 v57, v20, v57
	v_add_f32_e32 v49, v21, v49
	v_add_f32_e32 v52, v21, v52
	v_add_f32_e32 v55, v21, v55
	v_add_f32_e32 v58, v21, v58
	v_mul_f32_e32 v48, 0xbfb8aa3b, v48
	v_mul_f32_e32 v51, 0xbfb8aa3b, v51
	v_mul_f32_e32 v54, 0xbfb8aa3b, v54
	v_mul_f32_e32 v57, 0xbfb8aa3b, v57
	v_mul_f32_e32 v49, 0xbfb8aa3b, v49
	v_mul_f32_e32 v52, 0xbfb8aa3b, v52
	v_mul_f32_e32 v55, 0xbfb8aa3b, v55
	v_mul_f32_e32 v58, 0xbfb8aa3b, v58
	v_exp_f32_e32 v48, v48
	v_exp_f32_e32 v51, v51
	v_exp_f32_e32 v54, v54
	v_exp_f32_e32 v57, v57
	v_exp_f32_e32 v49, v49
	v_exp_f32_e32 v52, v52
	v_exp_f32_e32 v55, v55
	v_exp_f32_e32 v58, v58
	v_lshlrev_b32_e32 v50, 16, v148
	v_lshlrev_b32_e32 v53, 16, v149
	v_lshlrev_b32_e32 v56, 16, v150
	v_lshlrev_b32_e32 v59, 16, v151
	v_add_f32_e32 v48, 1.0, v48
	v_add_f32_e32 v51, 1.0, v51
	v_add_f32_e32 v54, 1.0, v54
	v_add_f32_e32 v57, 1.0, v57
	v_add_f32_e32 v49, 1.0, v49
	v_add_f32_e32 v52, 1.0, v52
	v_add_f32_e32 v55, 1.0, v55
	v_add_f32_e32 v58, 1.0, v58
	v_rcp_f32_e32 v48, v48
	v_rcp_f32_e32 v51, v51
	v_rcp_f32_e32 v54, v54
	v_rcp_f32_e32 v57, v57
	v_rcp_f32_e32 v49, v49
	v_rcp_f32_e32 v52, v52
	v_rcp_f32_e32 v55, v55
	v_rcp_f32_e32 v58, v58
	v_mul_f32_e32 v48, v24, v48
	v_mul_f32_e32 v51, v24, v51
	v_mul_f32_e32 v54, v24, v54
	v_mul_f32_e32 v57, v24, v57
	v_mul_f32_e32 v49, v49, v50
	v_mul_f32_e32 v52, v52, v53
	v_mul_f32_e32 v55, v55, v56
	v_mul_f32_e32 v58, v58, v59
	v_mul_f32_e32 v48, 0x3fb8aa3b, v48
	v_mul_f32_e32 v51, 0x3fb8aa3b, v51
	v_mul_f32_e32 v54, 0x3fb8aa3b, v54
	v_mul_f32_e32 v57, 0x3fb8aa3b, v57
	v_exp_f32_e32 v48, v48
	v_exp_f32_e32 v51, v51
	v_exp_f32_e32 v54, v54
	v_exp_f32_e32 v57, v57
	v_sub_f32_e32 v50, 1.0, v48
	v_sub_f32_e32 v53, 1.0, v51
	v_sub_f32_e32 v56, 1.0, v54
	v_sub_f32_e32 v59, 1.0, v57
	v_add_f32_e32 v88, 1.0, v48
	v_add_f32_e32 v90, 1.0, v51
	v_add_f32_e32 v92, 1.0, v54
	v_add_f32_e32 v94, 1.0, v57
	v_mul_f32_e32 v50, v50, v88
	v_mul_f32_e32 v53, v53, v90
	v_mul_f32_e32 v56, v56, v92
	v_mul_f32_e32 v59, v59, v94
	v_max_f32_e32 v50, 0, v50
	v_max_f32_e32 v53, 0, v53
	v_max_f32_e32 v56, 0, v56
	v_max_f32_e32 v59, 0, v59
	v_sqrt_f32_e32 v50, v50
	v_sqrt_f32_e32 v53, v53
	v_sqrt_f32_e32 v56, v56
	v_sqrt_f32_e32 v59, v59
	v_lshlrev_b32_e32 v60, 16, v89
	v_lshlrev_b32_e32 v63, 16, v91
	v_lshlrev_b32_e32 v66, 16, v93
	v_lshlrev_b32_e32 v69, 16, v95
	v_and_b32_e32 v61, 0xffff0000, v89
	v_and_b32_e32 v64, 0xffff0000, v91
	v_and_b32_e32 v67, 0xffff0000, v93
	v_and_b32_e32 v70, 0xffff0000, v95
	v_add_f32_e32 v60, v22, v60
	v_add_f32_e32 v63, v22, v63
	v_add_f32_e32 v66, v22, v66
	v_add_f32_e32 v69, v22, v69
	v_add_f32_e32 v61, v23, v61
	v_add_f32_e32 v64, v23, v64
	v_add_f32_e32 v67, v23, v67
	v_add_f32_e32 v70, v23, v70
	v_mul_f32_e32 v60, 0xbfb8aa3b, v60
	v_mul_f32_e32 v63, 0xbfb8aa3b, v63
	v_mul_f32_e32 v66, 0xbfb8aa3b, v66
	v_mul_f32_e32 v69, 0xbfb8aa3b, v69
	v_mul_f32_e32 v61, 0xbfb8aa3b, v61
	v_mul_f32_e32 v64, 0xbfb8aa3b, v64
	v_mul_f32_e32 v67, 0xbfb8aa3b, v67
	v_mul_f32_e32 v70, 0xbfb8aa3b, v70
	v_exp_f32_e32 v60, v60
	v_exp_f32_e32 v63, v63
	v_exp_f32_e32 v66, v66
	v_exp_f32_e32 v69, v69
	v_exp_f32_e32 v61, v61
	v_exp_f32_e32 v64, v64
	v_exp_f32_e32 v67, v67
	v_exp_f32_e32 v70, v70
	v_lshlrev_b32_e32 v62, 16, v148
	v_lshlrev_b32_e32 v65, 16, v149
	v_lshlrev_b32_e32 v68, 16, v150
	v_lshlrev_b32_e32 v71, 16, v151
	v_add_f32_e32 v60, 1.0, v60
	v_add_f32_e32 v63, 1.0, v63
	v_add_f32_e32 v66, 1.0, v66
	v_add_f32_e32 v69, 1.0, v69
	v_add_f32_e32 v61, 1.0, v61
	v_add_f32_e32 v64, 1.0, v64
	v_add_f32_e32 v67, 1.0, v67
	v_add_f32_e32 v70, 1.0, v70
	v_rcp_f32_e32 v60, v60
	v_rcp_f32_e32 v63, v63
	v_rcp_f32_e32 v66, v66
	v_rcp_f32_e32 v69, v69
	v_rcp_f32_e32 v61, v61
	v_rcp_f32_e32 v64, v64
	v_rcp_f32_e32 v67, v67
	v_rcp_f32_e32 v70, v70
	v_mul_f32_e32 v60, v25, v60
	v_mul_f32_e32 v63, v25, v63
	v_mul_f32_e32 v66, v25, v66
	v_mul_f32_e32 v69, v25, v69
	v_mul_f32_e32 v61, v61, v62
	v_mul_f32_e32 v64, v64, v65
	v_mul_f32_e32 v67, v67, v68
	v_mul_f32_e32 v70, v70, v71
	v_mul_f32_e32 v60, 0x3fb8aa3b, v60
	v_mul_f32_e32 v63, 0x3fb8aa3b, v63
	v_mul_f32_e32 v66, 0x3fb8aa3b, v66
	v_mul_f32_e32 v69, 0x3fb8aa3b, v69
	v_exp_f32_e32 v60, v60
	v_exp_f32_e32 v63, v63
	v_exp_f32_e32 v66, v66
	v_exp_f32_e32 v69, v69
	v_sub_f32_e32 v62, 1.0, v60
	v_sub_f32_e32 v65, 1.0, v63
	v_sub_f32_e32 v68, 1.0, v66
	v_sub_f32_e32 v71, 1.0, v69
	v_add_f32_e32 v89, 1.0, v60
	v_add_f32_e32 v91, 1.0, v63
	v_add_f32_e32 v93, 1.0, v66
	v_add_f32_e32 v95, 1.0, v69
	v_mul_f32_e32 v62, v62, v89
	v_mul_f32_e32 v65, v65, v91
	v_mul_f32_e32 v68, v68, v93
	v_mul_f32_e32 v71, v71, v95
	v_max_f32_e32 v62, 0, v62
	v_max_f32_e32 v65, 0, v65
	v_max_f32_e32 v68, 0, v68
	v_max_f32_e32 v71, 0, v71
	v_sqrt_f32_e32 v62, v62
	v_sqrt_f32_e32 v65, v65
	v_sqrt_f32_e32 v68, v68
	v_sqrt_f32_e32 v71, v71
	v_nop
	v_nop
	v_nop
	v_nop
	v_mul_f32_e32 v61, v61, v62
	v_mul_f32_e32 v64, v64, v65
	v_mul_f32_e32 v67, v67, v68
	v_mul_f32_e32 v70, v70, v71
	v_mul_f32_e32 v2, v2, v48
	v_fma_f32 v2, v49, v50, v2
	v_fma_f32 v3, v61, v19, v3
	v_mul_f32_e32 v18, v18, v48
	v_mul_f32_e32 v19, v19, v60
	v_mul_f32_e32 v2, v2, v51
; __device__ __forceinline__ float fast_sigmoid(float x) { return __builtin_amdgcn_rcpf(1.f + __builtin_amdgcn_exp2f(-1.4426950408889634f * x)); }
; __device__ __forceinline__ float bf2f(unsigned short h) { return __uint_as_float(((unsigned)h) << 16); }
; __device__ __forceinline__ float bflo(unsigned w) { return __uint_as_float(w << 16); }
; __device__ __forceinline__ float bfhi(unsigned w) { return __uint_as_float(w & 0xffff0000u); }
; __device__ __forceinline__ void scan_coef(float r, float i, float u, float sp8, float& a, float& b) { const float la = -sp8 * r; a = __expf(la); b = __builtin_amdgcn_sqrtf(fmaxf((1.f - a) * (1.f + a), 0.f)) * (i * u); }
; __global__ void __launch_bounds__(512) mega_fwd(Params P) {
;     ...
;                     for (int t = 0; t < 32; ++t) { const bf16_t* gp = XN + (size_t)(m0 + t) * 2048; const float u = bf2f(UC[(size_t)(m0 + t) * 512 + ch]);
;                         const u32x2 g4 = *(const u32x2*)(gp + ch * 4);
;                         float a, b; scan_coef(pg8::fast_sigmoid(bflo(g4.x) + brf), pg8::fast_sigmoid(bfhi(g4.x) + bif), u, spf, a, b); ef = a * ef + b; pf *= a;
;                         scan_coef(pg8::fast_sigmoid(bflo(g4.y) + brb), pg8::fast_sigmoid(bfhi(g4.y) + bib), u, spb, a, b); eb += pb * b; pb *= a; }
	v_fma_f32 v2, v52, v53, v2
	v_fma_f32 v3, v64, v19, v3
	v_mul_f32_e32 v18, v18, v51
	v_mul_f32_e32 v19, v19, v63
	v_mul_f32_e32 v2, v2, v54
	v_fma_f32 v2, v55, v56, v2
	v_fma_f32 v3, v67, v19, v3
	v_mul_f32_e32 v18, v18, v54
	v_mul_f32_e32 v19, v19, v66
	v_mul_f32_e32 v2, v2, v57
	v_fma_f32 v2, v58, v59, v2
	v_fma_f32 v3, v70, v19, v3
	v_mul_f32_e32 v18, v18, v57
	v_mul_f32_e32 v19, v19, v69
	v_lshlrev_b32_e32 v48, 16, v96
	v_lshlrev_b32_e32 v51, 16, v98
	v_lshlrev_b32_e32 v54, 16, v100
	v_lshlrev_b32_e32 v57, 16, v102
	v_and_b32_e32 v49, 0xffff0000, v96
	v_and_b32_e32 v52, 0xffff0000, v98
	v_and_b32_e32 v55, 0xffff0000, v100
	v_and_b32_e32 v58, 0xffff0000, v102
	v_add_f32_e32 v48, v20, v48
	v_add_f32_e32 v51, v20, v51
	v_add_f32_e32 v54, v20, v54
	v_add_f32_e32 v57, v20, v57
	v_add_f32_e32 v49, v21, v49
	v_add_f32_e32 v52, v21, v52
	v_add_f32_e32 v55, v21, v55
	v_add_f32_e32 v58, v21, v58
	v_mul_f32_e32 v48, 0xbfb8aa3b, v48
	v_mul_f32_e32 v51, 0xbfb8aa3b, v51
	v_mul_f32_e32 v54, 0xbfb8aa3b, v54
	v_mul_f32_e32 v57, 0xbfb8aa3b, v57
	v_mul_f32_e32 v49, 0xbfb8aa3b, v49
	v_mul_f32_e32 v52, 0xbfb8aa3b, v52
	v_mul_f32_e32 v55, 0xbfb8aa3b, v55
	v_mul_f32_e32 v58, 0xbfb8aa3b, v58
	v_exp_f32_e32 v48, v48
	v_exp_f32_e32 v51, v51
	v_exp_f32_e32 v54, v54
	v_exp_f32_e32 v57, v57
	v_exp_f32_e32 v49, v49
	v_exp_f32_e32 v52, v52
	v_exp_f32_e32 v55, v55
	v_exp_f32_e32 v58, v58
	v_lshlrev_b32_e32 v50, 16, v152
	v_lshlrev_b32_e32 v53, 16, v153
	v_lshlrev_b32_e32 v56, 16, v154
	v_lshlrev_b32_e32 v59, 16, v155
	v_add_f32_e32 v48, 1.0, v48
	v_add_f32_e32 v51, 1.0, v51
	v_add_f32_e32 v54, 1.0, v54
	v_add_f32_e32 v57, 1.0, v57
	v_add_f32_e32 v49, 1.0, v49
	v_add_f32_e32 v52, 1.0, v52
	v_add_f32_e32 v55, 1.0, v55
	v_add_f32_e32 v58, 1.0, v58
	v_rcp_f32_e32 v48, v48
	v_rcp_f32_e32 v51, v51
	v_rcp_f32_e32 v54, v54
	v_rcp_f32_e32 v57, v57
	v_rcp_f32_e32 v49, v49
	v_rcp_f32_e32 v52, v52
	v_rcp_f32_e32 v55, v55
	v_rcp_f32_e32 v58, v58
	v_mul_f32_e32 v48, v24, v48
	v_mul_f32_e32 v51, v24, v51
	v_mul_f32_e32 v54, v24, v54
	v_mul_f32_e32 v57, v24, v57
	v_mul_f32_e32 v49, v49, v50
	v_mul_f32_e32 v52, v52, v53
	v_mul_f32_e32 v55, v55, v56
	v_mul_f32_e32 v58, v58, v59
	v_mul_f32_e32 v48, 0x3fb8aa3b, v48
	v_mul_f32_e32 v51, 0x3fb8aa3b, v51
	v_mul_f32_e32 v54, 0x3fb8aa3b, v54
	v_mul_f32_e32 v57, 0x3fb8aa3b, v57
	v_exp_f32_e32 v48, v48
	v_exp_f32_e32 v51, v51
	v_exp_f32_e32 v54, v54
	v_exp_f32_e32 v57, v57
	v_sub_f32_e32 v50, 1.0, v48
	v_sub_f32_e32 v53, 1.0, v51
	v_sub_f32_e32 v56, 1.0, v54
	v_sub_f32_e32 v59, 1.0, v57
	v_add_f32_e32 v96, 1.0, v48
	v_add_f32_e32 v98, 1.0, v51
	v_add_f32_e32 v100, 1.0, v54
	v_add_f32_e32 v102, 1.0, v57
	v_mul_f32_e32 v50, v50, v96
	v_mul_f32_e32 v53, v53, v98
	v_mul_f32_e32 v56, v56, v100
	v_mul_f32_e32 v59, v59, v102
	v_max_f32_e32 v50, 0, v50
	v_max_f32_e32 v53, 0, v53
	v_max_f32_e32 v56, 0, v56
	v_max_f32_e32 v59, 0, v59
	v_sqrt_f32_e32 v50, v50
	v_sqrt_f32_e32 v53, v53
	v_sqrt_f32_e32 v56, v56
	v_sqrt_f32_e32 v59, v59
	v_lshlrev_b32_e32 v60, 16, v97
	v_lshlrev_b32_e32 v63, 16, v99
	v_lshlrev_b32_e32 v66, 16, v101
	v_lshlrev_b32_e32 v69, 16, v103
	v_and_b32_e32 v61, 0xffff0000, v97
	v_and_b32_e32 v64, 0xffff0000, v99
	v_and_b32_e32 v67, 0xffff0000, v101
	v_and_b32_e32 v70, 0xffff0000, v103
	v_add_f32_e32 v60, v22, v60
	v_add_f32_e32 v63, v22, v63
	v_add_f32_e32 v66, v22, v66
	v_add_f32_e32 v69, v22, v69
	v_add_f32_e32 v61, v23, v61
	v_add_f32_e32 v64, v23, v64
	v_add_f32_e32 v67, v23, v67
	v_add_f32_e32 v70, v23, v70
	v_mul_f32_e32 v60, 0xbfb8aa3b, v60
	v_mul_f32_e32 v63, 0xbfb8aa3b, v63
	v_mul_f32_e32 v66, 0xbfb8aa3b, v66
	v_mul_f32_e32 v69, 0xbfb8aa3b, v69
	v_mul_f32_e32 v61, 0xbfb8aa3b, v61
	v_mul_f32_e32 v64, 0xbfb8aa3b, v64
	v_mul_f32_e32 v67, 0xbfb8aa3b, v67
	v_mul_f32_e32 v70, 0xbfb8aa3b, v70
	v_exp_f32_e32 v60, v60
	v_exp_f32_e32 v63, v63
	v_exp_f32_e32 v66, v66
	v_exp_f32_e32 v69, v69
	v_exp_f32_e32 v61, v61
	v_exp_f32_e32 v64, v64
	v_exp_f32_e32 v67, v67
	v_exp_f32_e32 v70, v70
	v_lshlrev_b32_e32 v62, 16, v152
	v_lshlrev_b32_e32 v65, 16, v153
	v_lshlrev_b32_e32 v68, 16, v154
	v_lshlrev_b32_e32 v71, 16, v155
	v_add_f32_e32 v60, 1.0, v60
	v_add_f32_e32 v63, 1.0, v63
	v_add_f32_e32 v66, 1.0, v66
	v_add_f32_e32 v69, 1.0, v69
	v_add_f32_e32 v61, 1.0, v61
	v_add_f32_e32 v64, 1.0, v64
	v_add_f32_e32 v67, 1.0, v67
	v_add_f32_e32 v70, 1.0, v70
	v_rcp_f32_e32 v60, v60
	v_rcp_f32_e32 v63, v63
	v_rcp_f32_e32 v66, v66
	v_rcp_f32_e32 v69, v69
	v_rcp_f32_e32 v61, v61
	v_rcp_f32_e32 v64, v64
	v_rcp_f32_e32 v67, v67
	v_rcp_f32_e32 v70, v70
	v_mul_f32_e32 v60, v25, v60
	v_mul_f32_e32 v63, v25, v63
	v_mul_f32_e32 v66, v25, v66
	v_mul_f32_e32 v69, v25, v69
	v_mul_f32_e32 v61, v61, v62
	v_mul_f32_e32 v64, v64, v65
	v_mul_f32_e32 v67, v67, v68
	v_mul_f32_e32 v70, v70, v71
	v_mul_f32_e32 v60, 0x3fb8aa3b, v60
	v_mul_f32_e32 v63, 0x3fb8aa3b, v63
	v_mul_f32_e32 v66, 0x3fb8aa3b, v66
	v_mul_f32_e32 v69, 0x3fb8aa3b, v69
	v_exp_f32_e32 v60, v60
	v_exp_f32_e32 v63, v63
	v_exp_f32_e32 v66, v66
	v_exp_f32_e32 v69, v69
	v_sub_f32_e32 v62, 1.0, v60
	v_sub_f32_e32 v65, 1.0, v63
	v_sub_f32_e32 v68, 1.0, v66
	v_sub_f32_e32 v71, 1.0, v69
	v_add_f32_e32 v97, 1.0, v60
	v_add_f32_e32 v99, 1.0, v63
	v_add_f32_e32 v101, 1.0, v66
	v_add_f32_e32 v103, 1.0, v69
	v_mul_f32_e32 v62, v62, v97
	v_mul_f32_e32 v65, v65, v99
	v_mul_f32_e32 v68, v68, v101
	v_mul_f32_e32 v71, v71, v103
	v_max_f32_e32 v62, 0, v62
	v_max_f32_e32 v65, 0, v65
	v_max_f32_e32 v68, 0, v68
	v_max_f32_e32 v71, 0, v71
	v_sqrt_f32_e32 v62, v62
	v_sqrt_f32_e32 v65, v65
	v_sqrt_f32_e32 v68, v68
	v_sqrt_f32_e32 v71, v71
	v_nop
	v_nop
	v_nop
	v_nop
	v_mul_f32_e32 v61, v61, v62
	v_mul_f32_e32 v64, v64, v65
; __device__ __forceinline__ float fast_sigmoid(float x) { return __builtin_amdgcn_rcpf(1.f + __builtin_amdgcn_exp2f(-1.4426950408889634f * x)); }
; __device__ __forceinline__ float bf2f(unsigned short h) { return __uint_as_float(((unsigned)h) << 16); }
; __device__ __forceinline__ float bflo(unsigned w) { return __uint_as_float(w << 16); }
; __device__ __forceinline__ float bfhi(unsigned w) { return __uint_as_float(w & 0xffff0000u); }
; __device__ __forceinline__ void scan_coef(float r, float i, float u, float sp8, float& a, float& b) { const float la = -sp8 * r; a = __expf(la); b = __builtin_amdgcn_sqrtf(fmaxf((1.f - a) * (1.f + a), 0.f)) * (i * u); }
; __global__ void __launch_bounds__(512) mega_fwd(Params P) {
;     ...
;                     for (int t = 0; t < 32; ++t) { const bf16_t* gp = XN + (size_t)(m0 + t) * 2048; const float u = bf2f(UC[(size_t)(m0 + t) * 512 + ch]);
;                         const u32x2 g4 = *(const u32x2*)(gp + ch * 4);
;                         float a, b; scan_coef(pg8::fast_sigmoid(bflo(g4.x) + brf), pg8::fast_sigmoid(bfhi(g4.x) + bif), u, spf, a, b); ef = a * ef + b; pf *= a;
;                         scan_coef(pg8::fast_sigmoid(bflo(g4.y) + brb), pg8::fast_sigmoid(bfhi(g4.y) + bib), u, spb, a, b); eb += pb * b; pb *= a; }
	v_mul_f32_e32 v67, v67, v68
	v_mul_f32_e32 v70, v70, v71
	v_mul_f32_e32 v2, v2, v48
	v_fma_f32 v2, v49, v50, v2
	v_fma_f32 v3, v61, v19, v3
	v_mul_f32_e32 v18, v18, v48
	v_mul_f32_e32 v19, v19, v60
	v_mul_f32_e32 v2, v2, v51
	v_fma_f32 v2, v52, v53, v2
	v_fma_f32 v3, v64, v19, v3
	v_mul_f32_e32 v18, v18, v51
	v_mul_f32_e32 v19, v19, v63
	v_mul_f32_e32 v2, v2, v54
	v_fma_f32 v2, v55, v56, v2
	v_fma_f32 v3, v67, v19, v3
	v_mul_f32_e32 v18, v18, v54
	v_mul_f32_e32 v19, v19, v66
	v_mul_f32_e32 v2, v2, v57
	v_fma_f32 v2, v58, v59, v2
	v_fma_f32 v3, v70, v19, v3
	v_mul_f32_e32 v18, v18, v57
	v_mul_f32_e32 v19, v19, v69
	v_lshlrev_b32_e32 v48, 16, v104
	v_lshlrev_b32_e32 v51, 16, v106
	v_lshlrev_b32_e32 v54, 16, v108
	v_lshlrev_b32_e32 v57, 16, v110
	v_and_b32_e32 v49, 0xffff0000, v104
	v_and_b32_e32 v52, 0xffff0000, v106
	v_and_b32_e32 v55, 0xffff0000, v108
	v_and_b32_e32 v58, 0xffff0000, v110
	v_add_f32_e32 v48, v20, v48
	v_add_f32_e32 v51, v20, v51
	v_add_f32_e32 v54, v20, v54
	v_add_f32_e32 v57, v20, v57
	v_add_f32_e32 v49, v21, v49
	v_add_f32_e32 v52, v21, v52
	v_add_f32_e32 v55, v21, v55
	v_add_f32_e32 v58, v21, v58
	v_mul_f32_e32 v48, 0xbfb8aa3b, v48
	v_mul_f32_e32 v51, 0xbfb8aa3b, v51
	v_mul_f32_e32 v54, 0xbfb8aa3b, v54
	v_mul_f32_e32 v57, 0xbfb8aa3b, v57
	v_mul_f32_e32 v49, 0xbfb8aa3b, v49
	v_mul_f32_e32 v52, 0xbfb8aa3b, v52
	v_mul_f32_e32 v55, 0xbfb8aa3b, v55
	v_mul_f32_e32 v58, 0xbfb8aa3b, v58
	v_exp_f32_e32 v48, v48
	v_exp_f32_e32 v51, v51
	v_exp_f32_e32 v54, v54
	v_exp_f32_e32 v57, v57
	v_exp_f32_e32 v49, v49
	v_exp_f32_e32 v52, v52
	v_exp_f32_e32 v55, v55
	v_exp_f32_e32 v58, v58
	v_lshlrev_b32_e32 v50, 16, v156
	v_lshlrev_b32_e32 v53, 16, v157
	v_lshlrev_b32_e32 v56, 16, v158
	v_lshlrev_b32_e32 v59, 16, v159
	v_add_f32_e32 v48, 1.0, v48
	v_add_f32_e32 v51, 1.0, v51
	v_add_f32_e32 v54, 1.0, v54
	v_add_f32_e32 v57, 1.0, v57
	v_add_f32_e32 v49, 1.0, v49
	v_add_f32_e32 v52, 1.0, v52
	v_add_f32_e32 v55, 1.0, v55
	v_add_f32_e32 v58, 1.0, v58
	v_rcp_f32_e32 v48, v48
	v_rcp_f32_e32 v51, v51
	v_rcp_f32_e32 v54, v54
	v_rcp_f32_e32 v57, v57
	v_rcp_f32_e32 v49, v49
	v_rcp_f32_e32 v52, v52
	v_rcp_f32_e32 v55, v55
	v_rcp_f32_e32 v58, v58
	v_mul_f32_e32 v48, v24, v48
	v_mul_f32_e32 v51, v24, v51
	v_mul_f32_e32 v54, v24, v54
	v_mul_f32_e32 v57, v24, v57
	v_mul_f32_e32 v49, v49, v50
	v_mul_f32_e32 v52, v52, v53
	v_mul_f32_e32 v55, v55, v56
	v_mul_f32_e32 v58, v58, v59
	v_mul_f32_e32 v48, 0x3fb8aa3b, v48
	v_mul_f32_e32 v51, 0x3fb8aa3b, v51
	v_mul_f32_e32 v54, 0x3fb8aa3b, v54
	v_mul_f32_e32 v57, 0x3fb8aa3b, v57
	v_exp_f32_e32 v48, v48
	v_exp_f32_e32 v51, v51
	v_exp_f32_e32 v54, v54
	v_exp_f32_e32 v57, v57
	v_sub_f32_e32 v50, 1.0, v48
	v_sub_f32_e32 v53, 1.0, v51
	v_sub_f32_e32 v56, 1.0, v54
	v_sub_f32_e32 v59, 1.0, v57
	v_add_f32_e32 v104, 1.0, v48
	v_add_f32_e32 v106, 1.0, v51
	v_add_f32_e32 v108, 1.0, v54
	v_add_f32_e32 v110, 1.0, v57
	v_mul_f32_e32 v50, v50, v104
	v_mul_f32_e32 v53, v53, v106
	v_mul_f32_e32 v56, v56, v108
	v_mul_f32_e32 v59, v59, v110
	v_max_f32_e32 v50, 0, v50
	v_max_f32_e32 v53, 0, v53
	v_max_f32_e32 v56, 0, v56
	v_max_f32_e32 v59, 0, v59
	v_sqrt_f32_e32 v50, v50
	v_sqrt_f32_e32 v53, v53
	v_sqrt_f32_e32 v56, v56
	v_sqrt_f32_e32 v59, v59
	v_lshlrev_b32_e32 v60, 16, v105
	v_lshlrev_b32_e32 v63, 16, v107
	v_lshlrev_b32_e32 v66, 16, v109
	v_lshlrev_b32_e32 v69, 16, v111
	v_and_b32_e32 v61, 0xffff0000, v105
	v_and_b32_e32 v64, 0xffff0000, v107
	v_and_b32_e32 v67, 0xffff0000, v109
	v_and_b32_e32 v70, 0xffff0000, v111
	v_add_f32_e32 v60, v22, v60
	v_add_f32_e32 v63, v22, v63
	v_add_f32_e32 v66, v22, v66
	v_add_f32_e32 v69, v22, v69
	v_add_f32_e32 v61, v23, v61
	v_add_f32_e32 v64, v23, v64
	v_add_f32_e32 v67, v23, v67
	v_add_f32_e32 v70, v23, v70
	v_mul_f32_e32 v60, 0xbfb8aa3b, v60
	v_mul_f32_e32 v63, 0xbfb8aa3b, v63
	v_mul_f32_e32 v66, 0xbfb8aa3b, v66
	v_mul_f32_e32 v69, 0xbfb8aa3b, v69
	v_mul_f32_e32 v61, 0xbfb8aa3b, v61
	v_mul_f32_e32 v64, 0xbfb8aa3b, v64
	v_mul_f32_e32 v67, 0xbfb8aa3b, v67
	v_mul_f32_e32 v70, 0xbfb8aa3b, v70
	v_exp_f32_e32 v60, v60
	v_exp_f32_e32 v63, v63
	v_exp_f32_e32 v66, v66
	v_exp_f32_e32 v69, v69
	v_exp_f32_e32 v61, v61
	v_exp_f32_e32 v64, v64
	v_exp_f32_e32 v67, v67
	v_exp_f32_e32 v70, v70
	v_lshlrev_b32_e32 v62, 16, v156
	v_lshlrev_b32_e32 v65, 16, v157
	v_lshlrev_b32_e32 v68, 16, v158
	v_lshlrev_b32_e32 v71, 16, v159
	v_add_f32_e32 v60, 1.0, v60
	v_add_f32_e32 v63, 1.0, v63
	v_add_f32_e32 v66, 1.0, v66
	v_add_f32_e32 v69, 1.0, v69
	v_add_f32_e32 v61, 1.0, v61
	v_add_f32_e32 v64, 1.0, v64
	v_add_f32_e32 v67, 1.0, v67
	v_add_f32_e32 v70, 1.0, v70
	v_rcp_f32_e32 v60, v60
	v_rcp_f32_e32 v63, v63
	v_rcp_f32_e32 v66, v66
	v_rcp_f32_e32 v69, v69
	v_rcp_f32_e32 v61, v61
	v_rcp_f32_e32 v64, v64
	v_rcp_f32_e32 v67, v67
	v_rcp_f32_e32 v70, v70
	v_mul_f32_e32 v60, v25, v60
	v_mul_f32_e32 v63, v25, v63
	v_mul_f32_e32 v66, v25, v66
	v_mul_f32_e32 v69, v25, v69
	v_mul_f32_e32 v61, v61, v62
	v_mul_f32_e32 v64, v64, v65
	v_mul_f32_e32 v67, v67, v68
	v_mul_f32_e32 v70, v70, v71
	v_mul_f32_e32 v60, 0x3fb8aa3b, v60
	v_mul_f32_e32 v63, 0x3fb8aa3b, v63
	v_mul_f32_e32 v66, 0x3fb8aa3b, v66
	v_mul_f32_e32 v69, 0x3fb8aa3b, v69
	v_exp_f32_e32 v60, v60
	v_exp_f32_e32 v63, v63
	v_exp_f32_e32 v66, v66
	v_exp_f32_e32 v69, v69
	v_sub_f32_e32 v62, 1.0, v60
	v_sub_f32_e32 v65, 1.0, v63
	v_sub_f32_e32 v68, 1.0, v66
	v_sub_f32_e32 v71, 1.0, v69
	v_add_f32_e32 v105, 1.0, v60
	v_add_f32_e32 v107, 1.0, v63
	v_add_f32_e32 v109, 1.0, v66
	v_add_f32_e32 v111, 1.0, v69
	v_mul_f32_e32 v62, v62, v105
	v_mul_f32_e32 v65, v65, v107
	v_mul_f32_e32 v68, v68, v109
	v_mul_f32_e32 v71, v71, v111
	v_max_f32_e32 v62, 0, v62
	v_max_f32_e32 v65, 0, v65
	v_max_f32_e32 v68, 0, v68
	v_max_f32_e32 v71, 0, v71
	v_sqrt_f32_e32 v62, v62
	v_sqrt_f32_e32 v65, v65
	v_sqrt_f32_e32 v68, v68
	v_sqrt_f32_e32 v71, v71
	v_nop
	v_nop
	v_nop
	v_nop
	v_mul_f32_e32 v61, v61, v62
	v_mul_f32_e32 v64, v64, v65
	v_mul_f32_e32 v67, v67, v68
	v_mul_f32_e32 v70, v70, v71
	v_mul_f32_e32 v2, v2, v48
	v_fma_f32 v2, v49, v50, v2
	v_fma_f32 v3, v61, v19, v3
	v_mul_f32_e32 v18, v18, v48
	v_mul_f32_e32 v19, v19, v60
	v_mul_f32_e32 v2, v2, v51
	v_fma_f32 v2, v52, v53, v2
	v_fma_f32 v3, v64, v19, v3
	v_mul_f32_e32 v18, v18, v51
	v_mul_f32_e32 v19, v19, v63
	v_mul_f32_e32 v2, v2, v54
	v_fma_f32 v2, v55, v56, v2
	v_fma_f32 v3, v67, v19, v3
	v_mul_f32_e32 v18, v18, v54
	v_mul_f32_e32 v19, v19, v66
	v_mul_f32_e32 v2, v2, v57
	v_fma_f32 v2, v58, v59, v2
	v_fma_f32 v3, v70, v19, v3
	v_mul_f32_e32 v18, v18, v57
	v_mul_f32_e32 v19, v19, v69
	s_waitcnt vmcnt(24)
; __device__ __forceinline__ float fast_sigmoid(float x) { return __builtin_amdgcn_rcpf(1.f + __builtin_amdgcn_exp2f(-1.4426950408889634f * x)); }
; __device__ __forceinline__ float bf2f(unsigned short h) { return __uint_as_float(((unsigned)h) << 16); }
; __device__ __forceinline__ float bflo(unsigned w) { return __uint_as_float(w << 16); }
; __device__ __forceinline__ float bfhi(unsigned w) { return __uint_as_float(w & 0xffff0000u); }
; __device__ __forceinline__ void scan_coef(float r, float i, float u, float sp8, float& a, float& b) { const float la = -sp8 * r; a = __expf(la); b = __builtin_amdgcn_sqrtf(fmaxf((1.f - a) * (1.f + a), 0.f)) * (i * u); }
; __global__ void __launch_bounds__(512) mega_fwd(Params P) {
;     ...
;                     for (int t = 0; t < 32; ++t) { const bf16_t* gp = XN + (size_t)(m0 + t) * 2048; const float u = bf2f(UC[(size_t)(m0 + t) * 512 + ch]);
;                         const u32x2 g4 = *(const u32x2*)(gp + ch * 4);
;                         float a, b; scan_coef(pg8::fast_sigmoid(bflo(g4.x) + brf), pg8::fast_sigmoid(bfhi(g4.x) + bif), u, spf, a, b); ef = a * ef + b; pf *= a;
;                         scan_coef(pg8::fast_sigmoid(bflo(g4.y) + brb), pg8::fast_sigmoid(bfhi(g4.y) + bib), u, spb, a, b); eb += pb * b; pb *= a; }
	v_lshlrev_b32_e32 v48, 16, v112
	v_lshlrev_b32_e32 v51, 16, v114
	v_lshlrev_b32_e32 v54, 16, v116
	v_lshlrev_b32_e32 v57, 16, v118
	v_and_b32_e32 v49, 0xffff0000, v112
	v_and_b32_e32 v52, 0xffff0000, v114
	v_and_b32_e32 v55, 0xffff0000, v116
	v_and_b32_e32 v58, 0xffff0000, v118
	v_add_f32_e32 v48, v20, v48
	v_add_f32_e32 v51, v20, v51
	v_add_f32_e32 v54, v20, v54
	v_add_f32_e32 v57, v20, v57
	v_add_f32_e32 v49, v21, v49
	v_add_f32_e32 v52, v21, v52
	v_add_f32_e32 v55, v21, v55
	v_add_f32_e32 v58, v21, v58
	v_mul_f32_e32 v48, 0xbfb8aa3b, v48
	v_mul_f32_e32 v51, 0xbfb8aa3b, v51
	v_mul_f32_e32 v54, 0xbfb8aa3b, v54
	v_mul_f32_e32 v57, 0xbfb8aa3b, v57
	v_mul_f32_e32 v49, 0xbfb8aa3b, v49
	v_mul_f32_e32 v52, 0xbfb8aa3b, v52
	v_mul_f32_e32 v55, 0xbfb8aa3b, v55
	v_mul_f32_e32 v58, 0xbfb8aa3b, v58
	v_exp_f32_e32 v48, v48
	v_exp_f32_e32 v51, v51
	v_exp_f32_e32 v54, v54
	v_exp_f32_e32 v57, v57
	v_exp_f32_e32 v49, v49
	v_exp_f32_e32 v52, v52
	v_exp_f32_e32 v55, v55
	v_exp_f32_e32 v58, v58
	v_lshlrev_b32_e32 v50, 16, v160
	v_lshlrev_b32_e32 v53, 16, v161
	v_lshlrev_b32_e32 v56, 16, v162
	v_lshlrev_b32_e32 v59, 16, v163
	v_add_f32_e32 v48, 1.0, v48
	v_add_f32_e32 v51, 1.0, v51
	v_add_f32_e32 v54, 1.0, v54
	v_add_f32_e32 v57, 1.0, v57
	v_add_f32_e32 v49, 1.0, v49
	v_add_f32_e32 v52, 1.0, v52
	v_add_f32_e32 v55, 1.0, v55
	v_add_f32_e32 v58, 1.0, v58
	v_rcp_f32_e32 v48, v48
	v_rcp_f32_e32 v51, v51
	v_rcp_f32_e32 v54, v54
	v_rcp_f32_e32 v57, v57
	v_rcp_f32_e32 v49, v49
	v_rcp_f32_e32 v52, v52
	v_rcp_f32_e32 v55, v55
	v_rcp_f32_e32 v58, v58
	v_mul_f32_e32 v48, v24, v48
	v_mul_f32_e32 v51, v24, v51
	v_mul_f32_e32 v54, v24, v54
	v_mul_f32_e32 v57, v24, v57
	v_mul_f32_e32 v49, v49, v50
	v_mul_f32_e32 v52, v52, v53
	v_mul_f32_e32 v55, v55, v56
	v_mul_f32_e32 v58, v58, v59
	v_mul_f32_e32 v48, 0x3fb8aa3b, v48
	v_mul_f32_e32 v51, 0x3fb8aa3b, v51
	v_mul_f32_e32 v54, 0x3fb8aa3b, v54
	v_mul_f32_e32 v57, 0x3fb8aa3b, v57
	v_exp_f32_e32 v48, v48
	v_exp_f32_e32 v51, v51
	v_exp_f32_e32 v54, v54
	v_exp_f32_e32 v57, v57
	v_sub_f32_e32 v50, 1.0, v48
	v_sub_f32_e32 v53, 1.0, v51
	v_sub_f32_e32 v56, 1.0, v54
	v_sub_f32_e32 v59, 1.0, v57
	v_add_f32_e32 v112, 1.0, v48
	v_add_f32_e32 v114, 1.0, v51
	v_add_f32_e32 v116, 1.0, v54
	v_add_f32_e32 v118, 1.0, v57
	v_mul_f32_e32 v50, v50, v112
	v_mul_f32_e32 v53, v53, v114
	v_mul_f32_e32 v56, v56, v116
	v_mul_f32_e32 v59, v59, v118
	v_max_f32_e32 v50, 0, v50
	v_max_f32_e32 v53, 0, v53
	v_max_f32_e32 v56, 0, v56
	v_max_f32_e32 v59, 0, v59
	v_sqrt_f32_e32 v50, v50
	v_sqrt_f32_e32 v53, v53
	v_sqrt_f32_e32 v56, v56
	v_sqrt_f32_e32 v59, v59
	v_lshlrev_b32_e32 v60, 16, v113
	v_lshlrev_b32_e32 v63, 16, v115
	v_lshlrev_b32_e32 v66, 16, v117
	v_lshlrev_b32_e32 v69, 16, v119
	v_and_b32_e32 v61, 0xffff0000, v113
	v_and_b32_e32 v64, 0xffff0000, v115
	v_and_b32_e32 v67, 0xffff0000, v117
	v_and_b32_e32 v70, 0xffff0000, v119
	v_add_f32_e32 v60, v22, v60
	v_add_f32_e32 v63, v22, v63
	v_add_f32_e32 v66, v22, v66
	v_add_f32_e32 v69, v22, v69
	v_add_f32_e32 v61, v23, v61
	v_add_f32_e32 v64, v23, v64
	v_add_f32_e32 v67, v23, v67
	v_add_f32_e32 v70, v23, v70
	v_mul_f32_e32 v60, 0xbfb8aa3b, v60
	v_mul_f32_e32 v63, 0xbfb8aa3b, v63
	v_mul_f32_e32 v66, 0xbfb8aa3b, v66
	v_mul_f32_e32 v69, 0xbfb8aa3b, v69
	v_mul_f32_e32 v61, 0xbfb8aa3b, v61
	v_mul_f32_e32 v64, 0xbfb8aa3b, v64
	v_mul_f32_e32 v67, 0xbfb8aa3b, v67
	v_mul_f32_e32 v70, 0xbfb8aa3b, v70
	v_exp_f32_e32 v60, v60
	v_exp_f32_e32 v63, v63
	v_exp_f32_e32 v66, v66
	v_exp_f32_e32 v69, v69
	v_exp_f32_e32 v61, v61
	v_exp_f32_e32 v64, v64
	v_exp_f32_e32 v67, v67
	v_exp_f32_e32 v70, v70
	v_lshlrev_b32_e32 v62, 16, v160
	v_lshlrev_b32_e32 v65, 16, v161
	v_lshlrev_b32_e32 v68, 16, v162
	v_lshlrev_b32_e32 v71, 16, v163
	v_add_f32_e32 v60, 1.0, v60
	v_add_f32_e32 v63, 1.0, v63
	v_add_f32_e32 v66, 1.0, v66
	v_add_f32_e32 v69, 1.0, v69
	v_add_f32_e32 v61, 1.0, v61
	v_add_f32_e32 v64, 1.0, v64
	v_add_f32_e32 v67, 1.0, v67
	v_add_f32_e32 v70, 1.0, v70
	v_rcp_f32_e32 v60, v60
	v_rcp_f32_e32 v63, v63
	v_rcp_f32_e32 v66, v66
	v_rcp_f32_e32 v69, v69
	v_rcp_f32_e32 v61, v61
	v_rcp_f32_e32 v64, v64
	v_rcp_f32_e32 v67, v67
	v_rcp_f32_e32 v70, v70
	v_mul_f32_e32 v60, v25, v60
	v_mul_f32_e32 v63, v25, v63
	v_mul_f32_e32 v66, v25, v66
	v_mul_f32_e32 v69, v25, v69
	v_mul_f32_e32 v61, v61, v62
	v_mul_f32_e32 v64, v64, v65
	v_mul_f32_e32 v67, v67, v68
	v_mul_f32_e32 v70, v70, v71
	v_mul_f32_e32 v60, 0x3fb8aa3b, v60
	v_mul_f32_e32 v63, 0x3fb8aa3b, v63
	v_mul_f32_e32 v66, 0x3fb8aa3b, v66
	v_mul_f32_e32 v69, 0x3fb8aa3b, v69
	v_exp_f32_e32 v60, v60
	v_exp_f32_e32 v63, v63
	v_exp_f32_e32 v66, v66
	v_exp_f32_e32 v69, v69
	v_sub_f32_e32 v62, 1.0, v60
	v_sub_f32_e32 v65, 1.0, v63
	v_sub_f32_e32 v68, 1.0, v66
	v_sub_f32_e32 v71, 1.0, v69
	v_add_f32_e32 v113, 1.0, v60
	v_add_f32_e32 v115, 1.0, v63
	v_add_f32_e32 v117, 1.0, v66
	v_add_f32_e32 v119, 1.0, v69
	v_mul_f32_e32 v62, v62, v113
	v_mul_f32_e32 v65, v65, v115
	v_mul_f32_e32 v68, v68, v117
	v_mul_f32_e32 v71, v71, v119
	v_max_f32_e32 v62, 0, v62
	v_max_f32_e32 v65, 0, v65
	v_max_f32_e32 v68, 0, v68
	v_max_f32_e32 v71, 0, v71
	v_sqrt_f32_e32 v62, v62
	v_sqrt_f32_e32 v65, v65
	v_sqrt_f32_e32 v68, v68
	v_sqrt_f32_e32 v71, v71
	v_nop
	v_nop
	v_nop
	v_nop
	v_mul_f32_e32 v61, v61, v62
	v_mul_f32_e32 v64, v64, v65
	v_mul_f32_e32 v67, v67, v68
	v_mul_f32_e32 v70, v70, v71
	v_mul_f32_e32 v2, v2, v48
	v_fma_f32 v2, v49, v50, v2
	v_fma_f32 v3, v61, v19, v3
	v_mul_f32_e32 v18, v18, v48
	v_mul_f32_e32 v19, v19, v60
	v_mul_f32_e32 v2, v2, v51
	v_fma_f32 v2, v52, v53, v2
	v_fma_f32 v3, v64, v19, v3
	v_mul_f32_e32 v18, v18, v51
	v_mul_f32_e32 v19, v19, v63
	v_mul_f32_e32 v2, v2, v54
	v_fma_f32 v2, v55, v56, v2
	v_fma_f32 v3, v67, v19, v3
	v_mul_f32_e32 v18, v18, v54
	v_mul_f32_e32 v19, v19, v66
	v_mul_f32_e32 v2, v2, v57
	v_fma_f32 v2, v58, v59, v2
	v_fma_f32 v3, v70, v19, v3
	v_mul_f32_e32 v18, v18, v57
	v_mul_f32_e32 v19, v19, v69
	s_waitcnt vmcnt(16)
; __device__ __forceinline__ float fast_sigmoid(float x) { return __builtin_amdgcn_rcpf(1.f + __builtin_amdgcn_exp2f(-1.4426950408889634f * x)); }
; __device__ __forceinline__ float bf2f(unsigned short h) { return __uint_as_float(((unsigned)h) << 16); }
; __device__ __forceinline__ float bflo(unsigned w) { return __uint_as_float(w << 16); }
; __device__ __forceinline__ float bfhi(unsigned w) { return __uint_as_float(w & 0xffff0000u); }
; __device__ __forceinline__ void scan_coef(float r, float i, float u, float sp8, float& a, float& b) { const float la = -sp8 * r; a = __expf(la); b = __builtin_amdgcn_sqrtf(fmaxf((1.f - a) * (1.f + a), 0.f)) * (i * u); }
; __global__ void __launch_bounds__(512) mega_fwd(Params P) {
;     ...
;                     for (int t = 0; t < 32; ++t) { const bf16_t* gp = XN + (size_t)(m0 + t) * 2048; const float u = bf2f(UC[(size_t)(m0 + t) * 512 + ch]);
;                         const u32x2 g4 = *(const u32x2*)(gp + ch * 4);
;                         float a, b; scan_coef(pg8::fast_sigmoid(bflo(g4.x) + brf), pg8::fast_sigmoid(bfhi(g4.x) + bif), u, spf, a, b); ef = a * ef + b; pf *= a;
;                         scan_coef(pg8::fast_sigmoid(bflo(g4.y) + brb), pg8::fast_sigmoid(bfhi(g4.y) + bib), u, spb, a, b); eb += pb * b; pb *= a; }
	v_lshlrev_b32_e32 v48, 16, v120
	v_lshlrev_b32_e32 v51, 16, v122
	v_lshlrev_b32_e32 v54, 16, v124
	v_lshlrev_b32_e32 v57, 16, v126
	v_and_b32_e32 v49, 0xffff0000, v120
	v_and_b32_e32 v52, 0xffff0000, v122
	v_and_b32_e32 v55, 0xffff0000, v124
	v_and_b32_e32 v58, 0xffff0000, v126
	v_add_f32_e32 v48, v20, v48
	v_add_f32_e32 v51, v20, v51
	v_add_f32_e32 v54, v20, v54
	v_add_f32_e32 v57, v20, v57
	v_add_f32_e32 v49, v21, v49
	v_add_f32_e32 v52, v21, v52
	v_add_f32_e32 v55, v21, v55
	v_add_f32_e32 v58, v21, v58
	v_mul_f32_e32 v48, 0xbfb8aa3b, v48
	v_mul_f32_e32 v51, 0xbfb8aa3b, v51
	v_mul_f32_e32 v54, 0xbfb8aa3b, v54
	v_mul_f32_e32 v57, 0xbfb8aa3b, v57
	v_mul_f32_e32 v49, 0xbfb8aa3b, v49
	v_mul_f32_e32 v52, 0xbfb8aa3b, v52
	v_mul_f32_e32 v55, 0xbfb8aa3b, v55
	v_mul_f32_e32 v58, 0xbfb8aa3b, v58
	v_exp_f32_e32 v48, v48
	v_exp_f32_e32 v51, v51
	v_exp_f32_e32 v54, v54
	v_exp_f32_e32 v57, v57
	v_exp_f32_e32 v49, v49
	v_exp_f32_e32 v52, v52
	v_exp_f32_e32 v55, v55
	v_exp_f32_e32 v58, v58
	v_lshlrev_b32_e32 v50, 16, v164
	v_lshlrev_b32_e32 v53, 16, v165
	v_lshlrev_b32_e32 v56, 16, v166
	v_lshlrev_b32_e32 v59, 16, v167
	v_add_f32_e32 v48, 1.0, v48
	v_add_f32_e32 v51, 1.0, v51
	v_add_f32_e32 v54, 1.0, v54
	v_add_f32_e32 v57, 1.0, v57
	v_add_f32_e32 v49, 1.0, v49
	v_add_f32_e32 v52, 1.0, v52
	v_add_f32_e32 v55, 1.0, v55
	v_add_f32_e32 v58, 1.0, v58
	v_rcp_f32_e32 v48, v48
	v_rcp_f32_e32 v51, v51
	v_rcp_f32_e32 v54, v54
	v_rcp_f32_e32 v57, v57
	v_rcp_f32_e32 v49, v49
	v_rcp_f32_e32 v52, v52
	v_rcp_f32_e32 v55, v55
	v_rcp_f32_e32 v58, v58
	v_mul_f32_e32 v48, v24, v48
	v_mul_f32_e32 v51, v24, v51
	v_mul_f32_e32 v54, v24, v54
	v_mul_f32_e32 v57, v24, v57
	v_mul_f32_e32 v49, v49, v50
	v_mul_f32_e32 v52, v52, v53
	v_mul_f32_e32 v55, v55, v56
	v_mul_f32_e32 v58, v58, v59
	v_mul_f32_e32 v48, 0x3fb8aa3b, v48
	v_mul_f32_e32 v51, 0x3fb8aa3b, v51
	v_mul_f32_e32 v54, 0x3fb8aa3b, v54
	v_mul_f32_e32 v57, 0x3fb8aa3b, v57
	v_exp_f32_e32 v48, v48
	v_exp_f32_e32 v51, v51
	v_exp_f32_e32 v54, v54
	v_exp_f32_e32 v57, v57
	v_sub_f32_e32 v50, 1.0, v48
	v_sub_f32_e32 v53, 1.0, v51
	v_sub_f32_e32 v56, 1.0, v54
	v_sub_f32_e32 v59, 1.0, v57
	v_add_f32_e32 v120, 1.0, v48
	v_add_f32_e32 v122, 1.0, v51
	v_add_f32_e32 v124, 1.0, v54
	v_add_f32_e32 v126, 1.0, v57
	v_mul_f32_e32 v50, v50, v120
	v_mul_f32_e32 v53, v53, v122
	v_mul_f32_e32 v56, v56, v124
	v_mul_f32_e32 v59, v59, v126
	v_max_f32_e32 v50, 0, v50
	v_max_f32_e32 v53, 0, v53
	v_max_f32_e32 v56, 0, v56
	v_max_f32_e32 v59, 0, v59
	v_sqrt_f32_e32 v50, v50
	v_sqrt_f32_e32 v53, v53
	v_sqrt_f32_e32 v56, v56
	v_sqrt_f32_e32 v59, v59
	v_lshlrev_b32_e32 v60, 16, v121
	v_lshlrev_b32_e32 v63, 16, v123
	v_lshlrev_b32_e32 v66, 16, v125
	v_lshlrev_b32_e32 v69, 16, v127
	v_and_b32_e32 v61, 0xffff0000, v121
	v_and_b32_e32 v64, 0xffff0000, v123
	v_and_b32_e32 v67, 0xffff0000, v125
	v_and_b32_e32 v70, 0xffff0000, v127
	v_add_f32_e32 v60, v22, v60
	v_add_f32_e32 v63, v22, v63
	v_add_f32_e32 v66, v22, v66
	v_add_f32_e32 v69, v22, v69
	v_add_f32_e32 v61, v23, v61
	v_add_f32_e32 v64, v23, v64
	v_add_f32_e32 v67, v23, v67
	v_add_f32_e32 v70, v23, v70
	v_mul_f32_e32 v60, 0xbfb8aa3b, v60
	v_mul_f32_e32 v63, 0xbfb8aa3b, v63
	v_mul_f32_e32 v66, 0xbfb8aa3b, v66
	v_mul_f32_e32 v69, 0xbfb8aa3b, v69
	v_mul_f32_e32 v61, 0xbfb8aa3b, v61
	v_mul_f32_e32 v64, 0xbfb8aa3b, v64
	v_mul_f32_e32 v67, 0xbfb8aa3b, v67
	v_mul_f32_e32 v70, 0xbfb8aa3b, v70
	v_exp_f32_e32 v60, v60
	v_exp_f32_e32 v63, v63
	v_exp_f32_e32 v66, v66
	v_exp_f32_e32 v69, v69
	v_exp_f32_e32 v61, v61
	v_exp_f32_e32 v64, v64
	v_exp_f32_e32 v67, v67
	v_exp_f32_e32 v70, v70
	v_lshlrev_b32_e32 v62, 16, v164
	v_lshlrev_b32_e32 v65, 16, v165
	v_lshlrev_b32_e32 v68, 16, v166
	v_lshlrev_b32_e32 v71, 16, v167
	v_add_f32_e32 v60, 1.0, v60
	v_add_f32_e32 v63, 1.0, v63
	v_add_f32_e32 v66, 1.0, v66
	v_add_f32_e32 v69, 1.0, v69
	v_add_f32_e32 v61, 1.0, v61
	v_add_f32_e32 v64, 1.0, v64
	v_add_f32_e32 v67, 1.0, v67
	v_add_f32_e32 v70, 1.0, v70
	v_rcp_f32_e32 v60, v60
	v_rcp_f32_e32 v63, v63
	v_rcp_f32_e32 v66, v66
	v_rcp_f32_e32 v69, v69
	v_rcp_f32_e32 v61, v61
	v_rcp_f32_e32 v64, v64
	v_rcp_f32_e32 v67, v67
	v_rcp_f32_e32 v70, v70
	v_mul_f32_e32 v60, v25, v60
	v_mul_f32_e32 v63, v25, v63
	v_mul_f32_e32 v66, v25, v66
	v_mul_f32_e32 v69, v25, v69
	v_mul_f32_e32 v61, v61, v62
	v_mul_f32_e32 v64, v64, v65
	v_mul_f32_e32 v67, v67, v68
	v_mul_f32_e32 v70, v70, v71
	v_mul_f32_e32 v60, 0x3fb8aa3b, v60
	v_mul_f32_e32 v63, 0x3fb8aa3b, v63
	v_mul_f32_e32 v66, 0x3fb8aa3b, v66
	v_mul_f32_e32 v69, 0x3fb8aa3b, v69
	v_exp_f32_e32 v60, v60
	v_exp_f32_e32 v63, v63
	v_exp_f32_e32 v66, v66
	v_exp_f32_e32 v69, v69
	v_sub_f32_e32 v62, 1.0, v60
	v_sub_f32_e32 v65, 1.0, v63
	v_sub_f32_e32 v68, 1.0, v66
	v_sub_f32_e32 v71, 1.0, v69
	v_add_f32_e32 v121, 1.0, v60
	v_add_f32_e32 v123, 1.0, v63
	v_add_f32_e32 v125, 1.0, v66
	v_add_f32_e32 v127, 1.0, v69
	v_mul_f32_e32 v62, v62, v121
	v_mul_f32_e32 v65, v65, v123
	v_mul_f32_e32 v68, v68, v125
	v_mul_f32_e32 v71, v71, v127
	v_max_f32_e32 v62, 0, v62
	v_max_f32_e32 v65, 0, v65
	v_max_f32_e32 v68, 0, v68
	v_max_f32_e32 v71, 0, v71
	v_sqrt_f32_e32 v62, v62
	v_sqrt_f32_e32 v65, v65
	v_sqrt_f32_e32 v68, v68
	v_sqrt_f32_e32 v71, v71
	v_nop
	v_nop
	v_nop
	v_nop
	v_mul_f32_e32 v61, v61, v62
	v_mul_f32_e32 v64, v64, v65
	v_mul_f32_e32 v67, v67, v68
	v_mul_f32_e32 v70, v70, v71
	v_mul_f32_e32 v2, v2, v48
	v_fma_f32 v2, v49, v50, v2
	v_fma_f32 v3, v61, v19, v3
	v_mul_f32_e32 v18, v18, v48
	v_mul_f32_e32 v19, v19, v60
	v_mul_f32_e32 v2, v2, v51
	v_fma_f32 v2, v52, v53, v2
	v_fma_f32 v3, v64, v19, v3
	v_mul_f32_e32 v18, v18, v51
	v_mul_f32_e32 v19, v19, v63
	v_mul_f32_e32 v2, v2, v54
	v_fma_f32 v2, v55, v56, v2
	v_fma_f32 v3, v67, v19, v3
	v_mul_f32_e32 v18, v18, v54
	v_mul_f32_e32 v19, v19, v66
	v_mul_f32_e32 v2, v2, v57
	v_fma_f32 v2, v58, v59, v2
	v_fma_f32 v3, v70, v19, v3
	v_mul_f32_e32 v18, v18, v57
	v_mul_f32_e32 v19, v19, v69
	s_waitcnt vmcnt(8)
; __device__ __forceinline__ float fast_sigmoid(float x) { return __builtin_amdgcn_rcpf(1.f + __builtin_amdgcn_exp2f(-1.4426950408889634f * x)); }
; __device__ __forceinline__ float bf2f(unsigned short h) { return __uint_as_float(((unsigned)h) << 16); }
; __device__ __forceinline__ float bflo(unsigned w) { return __uint_as_float(w << 16); }
; __device__ __forceinline__ float bfhi(unsigned w) { return __uint_as_float(w & 0xffff0000u); }
; __device__ __forceinline__ void scan_coef(float r, float i, float u, float sp8, float& a, float& b) { const float la = -sp8 * r; a = __expf(la); b = __builtin_amdgcn_sqrtf(fmaxf((1.f - a) * (1.f + a), 0.f)) * (i * u); }
; __global__ void __launch_bounds__(512) mega_fwd(Params P) {
;     ...
;                     for (int t = 0; t < 32; ++t) { const bf16_t* gp = XN + (size_t)(m0 + t) * 2048; const float u = bf2f(UC[(size_t)(m0 + t) * 512 + ch]);
;                         const u32x2 g4 = *(const u32x2*)(gp + ch * 4);
;                         float a, b; scan_coef(pg8::fast_sigmoid(bflo(g4.x) + brf), pg8::fast_sigmoid(bfhi(g4.x) + bif), u, spf, a, b); ef = a * ef + b; pf *= a;
;                         scan_coef(pg8::fast_sigmoid(bflo(g4.y) + brb), pg8::fast_sigmoid(bfhi(g4.y) + bib), u, spb, a, b); eb += pb * b; pb *= a; }
	v_lshlrev_b32_e32 v48, 16, v128
	v_lshlrev_b32_e32 v51, 16, v130
	v_lshlrev_b32_e32 v54, 16, v132
	v_lshlrev_b32_e32 v57, 16, v134
	v_and_b32_e32 v49, 0xffff0000, v128
	v_and_b32_e32 v52, 0xffff0000, v130
	v_and_b32_e32 v55, 0xffff0000, v132
	v_and_b32_e32 v58, 0xffff0000, v134
	v_add_f32_e32 v48, v20, v48
	v_add_f32_e32 v51, v20, v51
	v_add_f32_e32 v54, v20, v54
	v_add_f32_e32 v57, v20, v57
	v_add_f32_e32 v49, v21, v49
	v_add_f32_e32 v52, v21, v52
	v_add_f32_e32 v55, v21, v55
	v_add_f32_e32 v58, v21, v58
	v_mul_f32_e32 v48, 0xbfb8aa3b, v48
	v_mul_f32_e32 v51, 0xbfb8aa3b, v51
	v_mul_f32_e32 v54, 0xbfb8aa3b, v54
	v_mul_f32_e32 v57, 0xbfb8aa3b, v57
	v_mul_f32_e32 v49, 0xbfb8aa3b, v49
	v_mul_f32_e32 v52, 0xbfb8aa3b, v52
	v_mul_f32_e32 v55, 0xbfb8aa3b, v55
	v_mul_f32_e32 v58, 0xbfb8aa3b, v58
	v_exp_f32_e32 v48, v48
	v_exp_f32_e32 v51, v51
	v_exp_f32_e32 v54, v54
	v_exp_f32_e32 v57, v57
	v_exp_f32_e32 v49, v49
	v_exp_f32_e32 v52, v52
	v_exp_f32_e32 v55, v55
	v_exp_f32_e32 v58, v58
	v_lshlrev_b32_e32 v50, 16, v168
	v_lshlrev_b32_e32 v53, 16, v169
	v_lshlrev_b32_e32 v56, 16, v170
	v_lshlrev_b32_e32 v59, 16, v171
	v_add_f32_e32 v48, 1.0, v48
	v_add_f32_e32 v51, 1.0, v51
	v_add_f32_e32 v54, 1.0, v54
	v_add_f32_e32 v57, 1.0, v57
	v_add_f32_e32 v49, 1.0, v49
	v_add_f32_e32 v52, 1.0, v52
	v_add_f32_e32 v55, 1.0, v55
	v_add_f32_e32 v58, 1.0, v58
	v_rcp_f32_e32 v48, v48
	v_rcp_f32_e32 v51, v51
	v_rcp_f32_e32 v54, v54
	v_rcp_f32_e32 v57, v57
	v_rcp_f32_e32 v49, v49
	v_rcp_f32_e32 v52, v52
	v_rcp_f32_e32 v55, v55
	v_rcp_f32_e32 v58, v58
	v_mul_f32_e32 v48, v24, v48
	v_mul_f32_e32 v51, v24, v51
	v_mul_f32_e32 v54, v24, v54
	v_mul_f32_e32 v57, v24, v57
	v_mul_f32_e32 v49, v49, v50
	v_mul_f32_e32 v52, v52, v53
	v_mul_f32_e32 v55, v55, v56
	v_mul_f32_e32 v58, v58, v59
	v_mul_f32_e32 v48, 0x3fb8aa3b, v48
	v_mul_f32_e32 v51, 0x3fb8aa3b, v51
	v_mul_f32_e32 v54, 0x3fb8aa3b, v54
	v_mul_f32_e32 v57, 0x3fb8aa3b, v57
	v_exp_f32_e32 v48, v48
	v_exp_f32_e32 v51, v51
	v_exp_f32_e32 v54, v54
	v_exp_f32_e32 v57, v57
	v_sub_f32_e32 v50, 1.0, v48
	v_sub_f32_e32 v53, 1.0, v51
	v_sub_f32_e32 v56, 1.0, v54
	v_sub_f32_e32 v59, 1.0, v57
	v_add_f32_e32 v128, 1.0, v48
	v_add_f32_e32 v130, 1.0, v51
	v_add_f32_e32 v132, 1.0, v54
	v_add_f32_e32 v134, 1.0, v57
	v_mul_f32_e32 v50, v50, v128
	v_mul_f32_e32 v53, v53, v130
	v_mul_f32_e32 v56, v56, v132
	v_mul_f32_e32 v59, v59, v134
	v_max_f32_e32 v50, 0, v50
	v_max_f32_e32 v53, 0, v53
	v_max_f32_e32 v56, 0, v56
	v_max_f32_e32 v59, 0, v59
	v_sqrt_f32_e32 v50, v50
	v_sqrt_f32_e32 v53, v53
	v_sqrt_f32_e32 v56, v56
	v_sqrt_f32_e32 v59, v59
	v_lshlrev_b32_e32 v60, 16, v129
	v_lshlrev_b32_e32 v63, 16, v131
	v_lshlrev_b32_e32 v66, 16, v133
	v_lshlrev_b32_e32 v69, 16, v135
	v_and_b32_e32 v61, 0xffff0000, v129
	v_and_b32_e32 v64, 0xffff0000, v131
	v_and_b32_e32 v67, 0xffff0000, v133
	v_and_b32_e32 v70, 0xffff0000, v135
	v_add_f32_e32 v60, v22, v60
	v_add_f32_e32 v63, v22, v63
	v_add_f32_e32 v66, v22, v66
	v_add_f32_e32 v69, v22, v69
	v_add_f32_e32 v61, v23, v61
	v_add_f32_e32 v64, v23, v64
	v_add_f32_e32 v67, v23, v67
	v_add_f32_e32 v70, v23, v70
	v_mul_f32_e32 v60, 0xbfb8aa3b, v60
	v_mul_f32_e32 v63, 0xbfb8aa3b, v63
	v_mul_f32_e32 v66, 0xbfb8aa3b, v66
	v_mul_f32_e32 v69, 0xbfb8aa3b, v69
	v_mul_f32_e32 v61, 0xbfb8aa3b, v61
	v_mul_f32_e32 v64, 0xbfb8aa3b, v64
	v_mul_f32_e32 v67, 0xbfb8aa3b, v67
	v_mul_f32_e32 v70, 0xbfb8aa3b, v70
	v_exp_f32_e32 v60, v60
	v_exp_f32_e32 v63, v63
	v_exp_f32_e32 v66, v66
	v_exp_f32_e32 v69, v69
	v_exp_f32_e32 v61, v61
	v_exp_f32_e32 v64, v64
	v_exp_f32_e32 v67, v67
	v_exp_f32_e32 v70, v70
	v_lshlrev_b32_e32 v62, 16, v168
	v_lshlrev_b32_e32 v65, 16, v169
	v_lshlrev_b32_e32 v68, 16, v170
	v_lshlrev_b32_e32 v71, 16, v171
	v_add_f32_e32 v60, 1.0, v60
	v_add_f32_e32 v63, 1.0, v63
	v_add_f32_e32 v66, 1.0, v66
	v_add_f32_e32 v69, 1.0, v69
	v_add_f32_e32 v61, 1.0, v61
	v_add_f32_e32 v64, 1.0, v64
	v_add_f32_e32 v67, 1.0, v67
	v_add_f32_e32 v70, 1.0, v70
	v_rcp_f32_e32 v60, v60
	v_rcp_f32_e32 v63, v63
	v_rcp_f32_e32 v66, v66
	v_rcp_f32_e32 v69, v69
	v_rcp_f32_e32 v61, v61
	v_rcp_f32_e32 v64, v64
	v_rcp_f32_e32 v67, v67
	v_rcp_f32_e32 v70, v70
	v_mul_f32_e32 v60, v25, v60
	v_mul_f32_e32 v63, v25, v63
	v_mul_f32_e32 v66, v25, v66
	v_mul_f32_e32 v69, v25, v69
	v_mul_f32_e32 v61, v61, v62
	v_mul_f32_e32 v64, v64, v65
	v_mul_f32_e32 v67, v67, v68
	v_mul_f32_e32 v70, v70, v71
	v_mul_f32_e32 v60, 0x3fb8aa3b, v60
	v_mul_f32_e32 v63, 0x3fb8aa3b, v63
	v_mul_f32_e32 v66, 0x3fb8aa3b, v66
	v_mul_f32_e32 v69, 0x3fb8aa3b, v69
	v_exp_f32_e32 v60, v60
	v_exp_f32_e32 v63, v63
	v_exp_f32_e32 v66, v66
	v_exp_f32_e32 v69, v69
	v_sub_f32_e32 v62, 1.0, v60
	v_sub_f32_e32 v65, 1.0, v63
	v_sub_f32_e32 v68, 1.0, v66
	v_sub_f32_e32 v71, 1.0, v69
	v_add_f32_e32 v129, 1.0, v60
	v_add_f32_e32 v131, 1.0, v63
	v_add_f32_e32 v133, 1.0, v66
	v_add_f32_e32 v135, 1.0, v69
	v_mul_f32_e32 v62, v62, v129
	v_mul_f32_e32 v65, v65, v131
	v_mul_f32_e32 v68, v68, v133
	v_mul_f32_e32 v71, v71, v135
	v_max_f32_e32 v62, 0, v62
	v_max_f32_e32 v65, 0, v65
	v_max_f32_e32 v68, 0, v68
	v_max_f32_e32 v71, 0, v71
	v_sqrt_f32_e32 v62, v62
	v_sqrt_f32_e32 v65, v65
	v_sqrt_f32_e32 v68, v68
	v_sqrt_f32_e32 v71, v71
	v_nop
	v_nop
	v_nop
	v_nop
	v_mul_f32_e32 v61, v61, v62
	v_mul_f32_e32 v64, v64, v65
	v_mul_f32_e32 v67, v67, v68
	v_mul_f32_e32 v70, v70, v71
	v_mul_f32_e32 v2, v2, v48
	v_fma_f32 v2, v49, v50, v2
	v_fma_f32 v3, v61, v19, v3
	v_mul_f32_e32 v18, v18, v48
	v_mul_f32_e32 v19, v19, v60
	v_mul_f32_e32 v2, v2, v51
	v_fma_f32 v2, v52, v53, v2
	v_fma_f32 v3, v64, v19, v3
	v_mul_f32_e32 v18, v18, v51
	v_mul_f32_e32 v19, v19, v63
	v_mul_f32_e32 v2, v2, v54
	v_fma_f32 v2, v55, v56, v2
	v_fma_f32 v3, v67, v19, v3
	v_mul_f32_e32 v18, v18, v54
	v_mul_f32_e32 v19, v19, v66
	v_mul_f32_e32 v2, v2, v57
	v_fma_f32 v2, v58, v59, v2
	v_fma_f32 v3, v70, v19, v3
	v_mul_f32_e32 v18, v18, v57
	v_mul_f32_e32 v19, v19, v69
	s_waitcnt vmcnt(0)
; __device__ __forceinline__ float fast_sigmoid(float x) { return __builtin_amdgcn_rcpf(1.f + __builtin_amdgcn_exp2f(-1.4426950408889634f * x)); }
; __device__ __forceinline__ float bf2f(unsigned short h) { return __uint_as_float(((unsigned)h) << 16); }
; __device__ __forceinline__ float bflo(unsigned w) { return __uint_as_float(w << 16); }
; __device__ __forceinline__ float bfhi(unsigned w) { return __uint_as_float(w & 0xffff0000u); }
; __device__ __forceinline__ void scan_coef(float r, float i, float u, float sp8, float& a, float& b) { const float la = -sp8 * r; a = __expf(la); b = __builtin_amdgcn_sqrtf(fmaxf((1.f - a) * (1.f + a), 0.f)) * (i * u); }
; __global__ void __launch_bounds__(512) mega_fwd(Params P) {
;     ...
;                     for (int t = 0; t < 32; ++t) { const bf16_t* gp = XN + (size_t)(m0 + t) * 2048; const float u = bf2f(UC[(size_t)(m0 + t) * 512 + ch]);
;                         const u32x2 g4 = *(const u32x2*)(gp + ch * 4);
;                         float a, b; scan_coef(pg8::fast_sigmoid(bflo(g4.x) + brf), pg8::fast_sigmoid(bfhi(g4.x) + bif), u, spf, a, b); ef = a * ef + b; pf *= a;
;                         scan_coef(pg8::fast_sigmoid(bflo(g4.y) + brb), pg8::fast_sigmoid(bfhi(g4.y) + bib), u, spb, a, b); eb += pb * b; pb *= a; }
;                     *(f32x4*)(SSUM + ((size_t)c * 512 + ch) * 4) = (f32x4){pf, ef, pb, eb};
	v_lshlrev_b32_e32 v48, 16, v136
	v_lshlrev_b32_e32 v51, 16, v138
	v_lshlrev_b32_e32 v54, 16, v140
	v_lshlrev_b32_e32 v57, 16, v142
	v_and_b32_e32 v49, 0xffff0000, v136
	v_and_b32_e32 v52, 0xffff0000, v138
	v_and_b32_e32 v55, 0xffff0000, v140
	v_and_b32_e32 v58, 0xffff0000, v142
	v_add_f32_e32 v48, v20, v48
	v_add_f32_e32 v51, v20, v51
	v_add_f32_e32 v54, v20, v54
	v_add_f32_e32 v57, v20, v57
	v_add_f32_e32 v49, v21, v49
	v_add_f32_e32 v52, v21, v52
	v_add_f32_e32 v55, v21, v55
	v_add_f32_e32 v58, v21, v58
	v_mul_f32_e32 v48, 0xbfb8aa3b, v48
	v_mul_f32_e32 v51, 0xbfb8aa3b, v51
	v_mul_f32_e32 v54, 0xbfb8aa3b, v54
	v_mul_f32_e32 v57, 0xbfb8aa3b, v57
	v_mul_f32_e32 v49, 0xbfb8aa3b, v49
	v_mul_f32_e32 v52, 0xbfb8aa3b, v52
	v_mul_f32_e32 v55, 0xbfb8aa3b, v55
	v_mul_f32_e32 v58, 0xbfb8aa3b, v58
	v_exp_f32_e32 v48, v48
	v_exp_f32_e32 v51, v51
	v_exp_f32_e32 v54, v54
	v_exp_f32_e32 v57, v57
	v_exp_f32_e32 v49, v49
	v_exp_f32_e32 v52, v52
	v_exp_f32_e32 v55, v55
	v_exp_f32_e32 v58, v58
	v_lshlrev_b32_e32 v50, 16, v172
	v_lshlrev_b32_e32 v53, 16, v173
	v_lshlrev_b32_e32 v56, 16, v174
	v_lshlrev_b32_e32 v59, 16, v175
	v_add_f32_e32 v48, 1.0, v48
	v_add_f32_e32 v51, 1.0, v51
	v_add_f32_e32 v54, 1.0, v54
	v_add_f32_e32 v57, 1.0, v57
	v_add_f32_e32 v49, 1.0, v49
	v_add_f32_e32 v52, 1.0, v52
	v_add_f32_e32 v55, 1.0, v55
	v_add_f32_e32 v58, 1.0, v58
	v_rcp_f32_e32 v48, v48
	v_rcp_f32_e32 v51, v51
	v_rcp_f32_e32 v54, v54
	v_rcp_f32_e32 v57, v57
	v_rcp_f32_e32 v49, v49
	v_rcp_f32_e32 v52, v52
	v_rcp_f32_e32 v55, v55
	v_rcp_f32_e32 v58, v58
	v_mul_f32_e32 v48, v24, v48
	v_mul_f32_e32 v51, v24, v51
	v_mul_f32_e32 v54, v24, v54
	v_mul_f32_e32 v57, v24, v57
	v_mul_f32_e32 v49, v49, v50
	v_mul_f32_e32 v52, v52, v53
	v_mul_f32_e32 v55, v55, v56
	v_mul_f32_e32 v58, v58, v59
	v_mul_f32_e32 v48, 0x3fb8aa3b, v48
	v_mul_f32_e32 v51, 0x3fb8aa3b, v51
	v_mul_f32_e32 v54, 0x3fb8aa3b, v54
	v_mul_f32_e32 v57, 0x3fb8aa3b, v57
	v_exp_f32_e32 v48, v48
	v_exp_f32_e32 v51, v51
	v_exp_f32_e32 v54, v54
	v_exp_f32_e32 v57, v57
	v_sub_f32_e32 v50, 1.0, v48
	v_sub_f32_e32 v53, 1.0, v51
	v_sub_f32_e32 v56, 1.0, v54
	v_sub_f32_e32 v59, 1.0, v57
	v_add_f32_e32 v136, 1.0, v48
	v_add_f32_e32 v138, 1.0, v51
	v_add_f32_e32 v140, 1.0, v54
	v_add_f32_e32 v142, 1.0, v57
	v_mul_f32_e32 v50, v50, v136
	v_mul_f32_e32 v53, v53, v138
	v_mul_f32_e32 v56, v56, v140
	v_mul_f32_e32 v59, v59, v142
	v_max_f32_e32 v50, 0, v50
	v_max_f32_e32 v53, 0, v53
	v_max_f32_e32 v56, 0, v56
	v_max_f32_e32 v59, 0, v59
	v_sqrt_f32_e32 v50, v50
	v_sqrt_f32_e32 v53, v53
	v_sqrt_f32_e32 v56, v56
	v_sqrt_f32_e32 v59, v59
	v_lshlrev_b32_e32 v60, 16, v137
	v_lshlrev_b32_e32 v63, 16, v139
	v_lshlrev_b32_e32 v66, 16, v141
	v_lshlrev_b32_e32 v69, 16, v143
	v_and_b32_e32 v61, 0xffff0000, v137
	v_and_b32_e32 v64, 0xffff0000, v139
	v_and_b32_e32 v67, 0xffff0000, v141
	v_and_b32_e32 v70, 0xffff0000, v143
	v_add_f32_e32 v60, v22, v60
	v_add_f32_e32 v63, v22, v63
	v_add_f32_e32 v66, v22, v66
	v_add_f32_e32 v69, v22, v69
	v_add_f32_e32 v61, v23, v61
	v_add_f32_e32 v64, v23, v64
	v_add_f32_e32 v67, v23, v67
	v_add_f32_e32 v70, v23, v70
	v_mul_f32_e32 v60, 0xbfb8aa3b, v60
	v_mul_f32_e32 v63, 0xbfb8aa3b, v63
	v_mul_f32_e32 v66, 0xbfb8aa3b, v66
	v_mul_f32_e32 v69, 0xbfb8aa3b, v69
	v_mul_f32_e32 v61, 0xbfb8aa3b, v61
	v_mul_f32_e32 v64, 0xbfb8aa3b, v64
	v_mul_f32_e32 v67, 0xbfb8aa3b, v67
	v_mul_f32_e32 v70, 0xbfb8aa3b, v70
	v_exp_f32_e32 v60, v60
	v_exp_f32_e32 v63, v63
	v_exp_f32_e32 v66, v66
	v_exp_f32_e32 v69, v69
	v_exp_f32_e32 v61, v61
	v_exp_f32_e32 v64, v64
	v_exp_f32_e32 v67, v67
	v_exp_f32_e32 v70, v70
	v_lshlrev_b32_e32 v62, 16, v172
	v_lshlrev_b32_e32 v65, 16, v173
	v_lshlrev_b32_e32 v68, 16, v174
	v_lshlrev_b32_e32 v71, 16, v175
	v_add_f32_e32 v60, 1.0, v60
	v_add_f32_e32 v63, 1.0, v63
	v_add_f32_e32 v66, 1.0, v66
	v_add_f32_e32 v69, 1.0, v69
	v_add_f32_e32 v61, 1.0, v61
	v_add_f32_e32 v64, 1.0, v64
	v_add_f32_e32 v67, 1.0, v67
	v_add_f32_e32 v70, 1.0, v70
	v_rcp_f32_e32 v60, v60
	v_rcp_f32_e32 v63, v63
	v_rcp_f32_e32 v66, v66
	v_rcp_f32_e32 v69, v69
	v_rcp_f32_e32 v61, v61
	v_rcp_f32_e32 v64, v64
	v_rcp_f32_e32 v67, v67
	v_rcp_f32_e32 v70, v70
	v_mul_f32_e32 v60, v25, v60
	v_mul_f32_e32 v63, v25, v63
	v_mul_f32_e32 v66, v25, v66
	v_mul_f32_e32 v69, v25, v69
	v_mul_f32_e32 v61, v61, v62
	v_mul_f32_e32 v64, v64, v65
	v_mul_f32_e32 v67, v67, v68
	v_mul_f32_e32 v70, v70, v71
	v_mul_f32_e32 v60, 0x3fb8aa3b, v60
	v_mul_f32_e32 v63, 0x3fb8aa3b, v63
	v_mul_f32_e32 v66, 0x3fb8aa3b, v66
	v_mul_f32_e32 v69, 0x3fb8aa3b, v69
	v_exp_f32_e32 v60, v60
	v_exp_f32_e32 v63, v63
	v_exp_f32_e32 v66, v66
	v_exp_f32_e32 v69, v69
	v_sub_f32_e32 v62, 1.0, v60
	v_sub_f32_e32 v65, 1.0, v63
	v_sub_f32_e32 v68, 1.0, v66
	v_sub_f32_e32 v71, 1.0, v69
	v_add_f32_e32 v137, 1.0, v60
	v_add_f32_e32 v139, 1.0, v63
	v_add_f32_e32 v141, 1.0, v66
	v_add_f32_e32 v143, 1.0, v69
	v_mul_f32_e32 v62, v62, v137
	v_mul_f32_e32 v65, v65, v139
	v_mul_f32_e32 v68, v68, v141
	v_mul_f32_e32 v71, v71, v143
	v_max_f32_e32 v62, 0, v62
	v_max_f32_e32 v65, 0, v65
	v_max_f32_e32 v68, 0, v68
	v_max_f32_e32 v71, 0, v71
	v_sqrt_f32_e32 v62, v62
	v_sqrt_f32_e32 v65, v65
	v_sqrt_f32_e32 v68, v68
	v_sqrt_f32_e32 v71, v71
	v_nop
	v_nop
	v_nop
	v_nop
	v_mul_f32_e32 v61, v61, v62
	v_mul_f32_e32 v64, v64, v65
	v_mul_f32_e32 v67, v67, v68
	v_mul_f32_e32 v70, v70, v71
	v_mul_f32_e32 v2, v2, v48
	v_fma_f32 v2, v49, v50, v2
	v_fma_f32 v3, v61, v19, v3
	v_mul_f32_e32 v18, v18, v48
	v_mul_f32_e32 v19, v19, v60
	v_mul_f32_e32 v2, v2, v51
	v_fma_f32 v2, v52, v53, v2
	v_fma_f32 v3, v64, v19, v3
	v_mul_f32_e32 v18, v18, v51
	v_mul_f32_e32 v19, v19, v63
	v_mul_f32_e32 v2, v2, v54
	v_fma_f32 v2, v55, v56, v2
	v_fma_f32 v3, v67, v19, v3
	v_mul_f32_e32 v18, v18, v54
	v_mul_f32_e32 v19, v19, v66
	v_mul_f32_e32 v2, v2, v57
	v_fma_f32 v2, v58, v59, v2
	v_fma_f32 v3, v70, v19, v3
	v_mul_f32_e32 v18, v18, v57
	v_mul_f32_e32 v19, v19, v69
	s_ashr_i32 s55, s54, 31
	s_lshl_b64 s[38:39], s[54:55], 13
	v_lshl_add_u64 v[16:17], v[14:15], 0, s[38:39]
	v_readlane_b32 s38, v254, 62
	v_add_co_u32_e32 v16, vcc, 0xfe980000, v16
	s_add_i32 s54, s54, s3
	s_add_i32 s29, s29, s38
	s_add_i32 s44, s44, s38
	v_mov_b32_e32 v0, v18
	v_mov_b32_e32 v1, v2
	v_mov_b32_e32 v2, v19
	v_addc_co_u32_e32 v17, vcc, -1, v17, vcc
	s_cmpk_gt_i32 s54, 0x103f
	global_store_dwordx4 v[16:17], v[0:3], off
	s_cbranch_scc0 .LBB0_999

.LBB0_1660:
	v_add_u32_e32 v0, s44, v0
	v_add_co_u32_e32 v4, vcc, 0xff500000, v2
	s_nop 1
	v_addc_co_u32_e32 v5, vcc, -1, v3, vcc
	global_load_dword v100, v[4:5], off
	v_add_co_u32_e32 v4, vcc, 0xff528000, v2
	s_nop 1
	v_addc_co_u32_e32 v5, vcc, -1, v3, vcc
	global_load_dword v101, v[4:5], off
	v_add_co_u32_e32 v4, vcc, 0xff550000, v2
	s_nop 1
	v_addc_co_u32_e32 v5, vcc, -1, v3, vcc
	global_load_dword v102, v[4:5], off
	v_add_co_u32_e32 v4, vcc, 0xff578000, v2
	s_nop 1
	v_addc_co_u32_e32 v5, vcc, -1, v3, vcc
	global_load_dword v103, v[4:5], off
	v_add_co_u32_e32 v4, vcc, 0xff5a0000, v2
	s_nop 1
	v_addc_co_u32_e32 v5, vcc, -1, v3, vcc
	global_load_dword v104, v[4:5], off
	v_add_co_u32_e32 v4, vcc, 0xff5c8000, v2
	s_nop 1
	v_addc_co_u32_e32 v5, vcc, -1, v3, vcc
	global_load_dword v105, v[4:5], off
	v_add_co_u32_e32 v4, vcc, 0xff5f0000, v2
	s_nop 1
	v_addc_co_u32_e32 v5, vcc, -1, v3, vcc
	global_load_dword v106, v[4:5], off
	v_add_co_u32_e32 v4, vcc, 0xff618000, v2
	s_nop 1
	v_addc_co_u32_e32 v5, vcc, -1, v3, vcc
	global_load_dword v107, v[4:5], off
	v_add_co_u32_e32 v4, vcc, 0xff640000, v2
	s_nop 1
	v_addc_co_u32_e32 v5, vcc, -1, v3, vcc
	global_load_dword v108, v[4:5], off
	v_add_co_u32_e32 v4, vcc, 0xff668000, v2
	s_nop 1
	v_addc_co_u32_e32 v5, vcc, -1, v3, vcc
	global_load_dword v109, v[4:5], off
	v_add_co_u32_e32 v4, vcc, 0xff690000, v2
	s_nop 1
	v_addc_co_u32_e32 v5, vcc, -1, v3, vcc
	global_load_dword v110, v[4:5], off
	v_add_co_u32_e32 v4, vcc, 0xff6b8000, v2
	s_nop 1
	v_addc_co_u32_e32 v5, vcc, -1, v3, vcc
	global_load_dword v111, v[4:5], off
	v_add_co_u32_e32 v4, vcc, 0xff6e0000, v2
	s_nop 1
	v_addc_co_u32_e32 v5, vcc, -1, v3, vcc
	global_load_dword v112, v[4:5], off
	v_add_co_u32_e32 v4, vcc, 0xff708000, v2
	s_nop 1
	v_addc_co_u32_e32 v5, vcc, -1, v3, vcc
	global_load_dword v113, v[4:5], off
	v_add_co_u32_e32 v4, vcc, 0xff730000, v2
	s_nop 1
	v_addc_co_u32_e32 v5, vcc, -1, v3, vcc
	global_load_dword v114, v[4:5], off
	v_add_co_u32_e32 v4, vcc, 0xff758000, v2
	s_nop 1
	v_addc_co_u32_e32 v5, vcc, -1, v3, vcc
	global_load_dword v115, v[4:5], off
	v_add_co_u32_e32 v4, vcc, 0xff780000, v2
	s_nop 1
	v_addc_co_u32_e32 v5, vcc, -1, v3, vcc
	global_load_dword v116, v[4:5], off
	v_add_co_u32_e32 v4, vcc, 0xff7a8000, v2
	s_nop 1
	v_addc_co_u32_e32 v5, vcc, -1, v3, vcc
	global_load_dword v117, v[4:5], off
	v_add_co_u32_e32 v4, vcc, 0xff7d0000, v2
	s_nop 1
	v_addc_co_u32_e32 v5, vcc, -1, v3, vcc
	global_load_dword v118, v[4:5], off
	v_add_co_u32_e32 v4, vcc, 0xff7f8000, v2
	s_nop 1
	v_addc_co_u32_e32 v5, vcc, -1, v3, vcc
	global_load_dword v119, v[4:5], off
	v_add_co_u32_e32 v4, vcc, 0xff820000, v2
	s_nop 1
	v_addc_co_u32_e32 v5, vcc, -1, v3, vcc
	global_load_dword v120, v[4:5], off
	v_add_co_u32_e32 v4, vcc, 0xff848000, v2
	s_nop 1
	v_addc_co_u32_e32 v5, vcc, -1, v3, vcc
	global_load_dword v121, v[4:5], off
	v_add_co_u32_e32 v4, vcc, 0xff870000, v2
	s_nop 1
	v_addc_co_u32_e32 v5, vcc, -1, v3, vcc
	global_load_dword v122, v[4:5], off
	v_add_co_u32_e32 v4, vcc, 0xff898000, v2
	s_nop 1
	v_addc_co_u32_e32 v5, vcc, -1, v3, vcc
	global_load_dword v123, v[4:5], off
	v_add_co_u32_e32 v4, vcc, 0xff8c0000, v2
	s_nop 1
	v_addc_co_u32_e32 v5, vcc, -1, v3, vcc
	global_load_dword v124, v[4:5], off
	v_add_co_u32_e32 v4, vcc, 0xff8e8000, v2
	s_nop 1
	v_addc_co_u32_e32 v5, vcc, -1, v3, vcc
	global_load_dword v125, v[4:5], off
	v_add_co_u32_e32 v4, vcc, 0xff910000, v2
	s_nop 1
	v_addc_co_u32_e32 v5, vcc, -1, v3, vcc
	global_load_dword v126, v[4:5], off
	v_add_co_u32_e32 v4, vcc, 0xff938000, v2
	s_nop 1
	v_addc_co_u32_e32 v5, vcc, -1, v3, vcc
	global_load_dword v127, v[4:5], off
	v_add_co_u32_e32 v4, vcc, 0xff960000, v2
	s_nop 1
	v_addc_co_u32_e32 v5, vcc, -1, v3, vcc
	global_load_dword v128, v[4:5], off
	v_add_co_u32_e32 v4, vcc, 0xff988000, v2
	s_nop 1
	v_addc_co_u32_e32 v5, vcc, -1, v3, vcc
	global_load_dword v129, v[4:5], off
	v_add_co_u32_e32 v4, vcc, 0xff9b0000, v2
	s_nop 1
	v_addc_co_u32_e32 v5, vcc, -1, v3, vcc
	global_load_dword v130, v[4:5], off
	v_add_co_u32_e32 v4, vcc, 0xff9d8000, v2
	s_nop 1
	v_addc_co_u32_e32 v5, vcc, -1, v3, vcc
	global_load_dword v131, v[4:5], off
	s_waitcnt vmcnt(31)
	v_add_f32_e32 v1, 0, v100
	s_waitcnt vmcnt(30)
	v_add_f32_e32 v1, v1, v101
	s_waitcnt vmcnt(29)
	v_add_f32_e32 v1, v1, v102
	s_waitcnt vmcnt(28)
	v_add_f32_e32 v1, v1, v103
	s_waitcnt vmcnt(27)
	v_add_f32_e32 v1, v1, v104
	s_waitcnt vmcnt(26)
	v_add_f32_e32 v1, v1, v105
	s_waitcnt vmcnt(25)
	v_add_f32_e32 v1, v1, v106
	s_waitcnt vmcnt(24)
	v_add_f32_e32 v1, v1, v107
	s_waitcnt vmcnt(23)
	v_add_f32_e32 v1, v1, v108
	s_waitcnt vmcnt(22)
	v_add_f32_e32 v1, v1, v109
	s_waitcnt vmcnt(21)
	v_add_f32_e32 v1, v1, v110
	s_waitcnt vmcnt(20)
	v_add_f32_e32 v1, v1, v111
	s_waitcnt vmcnt(19)
	v_add_f32_e32 v1, v1, v112
	s_waitcnt vmcnt(18)
	v_add_f32_e32 v1, v1, v113
	s_waitcnt vmcnt(17)
	v_add_f32_e32 v1, v1, v114
	s_waitcnt vmcnt(16)
	v_add_f32_e32 v1, v1, v115
	s_waitcnt vmcnt(15)
	v_add_f32_e32 v1, v1, v116
	s_waitcnt vmcnt(14)
	v_add_f32_e32 v1, v1, v117
	s_waitcnt vmcnt(13)
	v_add_f32_e32 v1, v1, v118
	s_waitcnt vmcnt(12)
	v_add_f32_e32 v1, v1, v119
	s_waitcnt vmcnt(11)
	v_add_f32_e32 v1, v1, v120
	s_waitcnt vmcnt(10)
	v_add_f32_e32 v1, v1, v121
	s_waitcnt vmcnt(9)
	v_add_f32_e32 v1, v1, v122
	s_waitcnt vmcnt(8)
	v_add_f32_e32 v1, v1, v123
	s_waitcnt vmcnt(7)
	v_add_f32_e32 v1, v1, v124
	s_waitcnt vmcnt(6)
	v_add_f32_e32 v1, v1, v125
	s_waitcnt vmcnt(5)
	v_add_f32_e32 v1, v1, v126
	s_waitcnt vmcnt(4)
	v_add_f32_e32 v1, v1, v127
	s_waitcnt vmcnt(3)
	v_add_f32_e32 v1, v1, v128
	s_waitcnt vmcnt(2)
	v_add_f32_e32 v1, v1, v129
	s_waitcnt vmcnt(1)
	v_add_f32_e32 v1, v1, v130
	s_waitcnt vmcnt(0)
	v_add_f32_e32 v1, v1, v131
	v_fmamk_f32 v1, v1, 0x3a000000, v196
	v_cmp_gt_f32_e32 vcc, s78, v1
	v_mul_f32_e32 v4, 0x4b800000, v1
	s_nop 0
	v_cndmask_b32_e32 v1, v1, v4, vcc
	v_rsq_f32_e32 v1, v1
	s_nop 0
	v_mul_f32_e32 v4, 0x45800000, v1
	v_cndmask_b32_e32 v1, v1, v4, vcc
	v_cmp_lt_i32_e32 vcc, s91, v0
	global_store_dword v[2:3], v1, off
	v_lshl_add_u64 v[2:3], v[2:3], 0, s[46:47]
	s_or_b64 s[48:49], vcc, s[48:49]
	s_andn2_b64 exec, exec, s[48:49]
	s_cbranch_execnz .LBB0_1660
